# seg5 epilogue rewritten by hand: 16 independent groups, wave w enters at group 2w (rotated order) so 8 waves overlap I-cache misses of once-executed code; math bit-identical
# speedup vs baseline: 1.0395x; 1.0395x over previous
;     __device__ __forceinline__ void operator()(const f32x4 (&acc)[2][2][4][2], const pg8::Unit& u, int wr, int wc, int fr, int fq) const {
;         const int seg = u.pn >> 2;
;         const int row0 = u.pm * 256 + wr * 64 + fr, col0 = (u.pn & 3) * 256 + wc * 32 + 8 * fq;
;         if (seg == 5) {
; #pragma unroll
;             for (int bj = 0; bj < 2; ++bj) {
;                 const int col = col0 + bj * 128;
;                 float lb[8];
; #pragma unroll
;                 for (int j = 0; j < 8; ++j) lb[j] = __builtin_amdgcn_rcpf(1.f + __expf(lbl[1024 + col + j] - lbl[col + j]));
.LBB0_94:
	s_lshl_b32 s27, s4, 8
	s_lshl_b32 s3, s36, 8
	s_ashr_i32 s29, s36, 2
	s_add_i32 s27, s27, s88
	s_and_b32 s3, s3, 0x300
	v_or_b32_e32 v154, s27, v171
	v_or_b32_e32 v178, s3, v173
	s_mov_b64 s[40:41], -1
	s_mov_b64 s[38:39], 0
	s_cmp_lt_i32 s29, 5
	s_mov_b64 s[4:5], 0
	s_cbranch_scc1 .LBB0_104
	s_cmp_eq_u32 s29, 5
	s_mov_b64 s[4:5], -1
	s_cbranch_scc0 .LBB0_97
	v_readlane_b32 s52, v250, 9
	v_readlane_b32 s53, v250, 10
	v_lshlrev_b32_e32 v144, 2, v178
	v_add_u32_e32 v155, 0x1000, v144
	s_mov_b32 s98, 0xbfb8aa3b
	s_mov_b32 s99, 0x3377d1cf
	s_mov_b32 s100, 0x3fb8aa3b
	s_nop 1
	global_load_dwordx4 v[128:131], v144, s[52:53]
	global_load_dwordx4 v[132:135], v144, s[52:53] offset:16
	global_load_dwordx4 v[156:159], v155, s[52:53]
	global_load_dwordx4 v[160:163], v155, s[52:53] offset:16
	global_load_dwordx4 v[164:167], v144, s[52:53] offset:512
	global_load_dwordx4 v[180:183], v144, s[52:53] offset:528
	global_load_dwordx4 v[184:187], v155, s[52:53] offset:512
	global_load_dwordx4 v[188:191], v155, s[52:53] offset:528
	v_lshlrev_b32_e32 v179, 11, v154
	v_lshl_add_u32 v179, v178, 1, v179
	v_readfirstlane_b32 s3, v200
	s_waitcnt vmcnt(0)
	v_sub_f32_e32 v156, v156, v128
	v_sub_f32_e32 v157, v157, v129
	v_sub_f32_e32 v158, v158, v130
	v_sub_f32_e32 v159, v159, v131
	v_sub_f32_e32 v160, v160, v132
	v_sub_f32_e32 v161, v161, v133
	v_sub_f32_e32 v162, v162, v134
	v_sub_f32_e32 v163, v163, v135
	v_sub_f32_e32 v184, v184, v164
	v_sub_f32_e32 v185, v185, v165
	v_sub_f32_e32 v186, v186, v166
	v_sub_f32_e32 v187, v187, v167
	v_sub_f32_e32 v188, v188, v180
	v_sub_f32_e32 v189, v189, v181
	v_sub_f32_e32 v190, v190, v182
	v_sub_f32_e32 v191, v191, v183
	v_mul_f32_e32 v156, s100, v156
	v_mul_f32_e32 v157, s100, v157
	v_mul_f32_e32 v158, s100, v158
	v_mul_f32_e32 v159, s100, v159
	v_mul_f32_e32 v160, s100, v160
	v_mul_f32_e32 v161, s100, v161
	v_mul_f32_e32 v162, s100, v162
	v_mul_f32_e32 v163, s100, v163
	v_mul_f32_e32 v184, s100, v184
	v_mul_f32_e32 v185, s100, v185
	v_mul_f32_e32 v186, s100, v186
	v_mul_f32_e32 v187, s100, v187
	v_mul_f32_e32 v188, s100, v188
	v_mul_f32_e32 v189, s100, v189
	v_mul_f32_e32 v190, s100, v190
	v_mul_f32_e32 v191, s100, v191
	v_exp_f32_e32 v156, v156
	v_exp_f32_e32 v157, v157
	v_exp_f32_e32 v158, v158
	v_exp_f32_e32 v159, v159
	v_exp_f32_e32 v160, v160
	v_exp_f32_e32 v161, v161
	v_exp_f32_e32 v162, v162
	v_exp_f32_e32 v163, v163
	v_exp_f32_e32 v184, v184
	v_exp_f32_e32 v185, v185
	v_exp_f32_e32 v186, v186
	v_exp_f32_e32 v187, v187
	v_exp_f32_e32 v188, v188
	v_exp_f32_e32 v189, v189
	v_exp_f32_e32 v190, v190
	v_exp_f32_e32 v191, v191
	v_add_f32_e32 v156, 1.0, v156
	v_add_f32_e32 v157, 1.0, v157
	v_add_f32_e32 v158, 1.0, v158
	v_add_f32_e32 v159, 1.0, v159
	v_add_f32_e32 v160, 1.0, v160
	v_add_f32_e32 v161, 1.0, v161
	v_add_f32_e32 v162, 1.0, v162
	v_add_f32_e32 v163, 1.0, v163
	v_add_f32_e32 v184, 1.0, v184
	v_add_f32_e32 v185, 1.0, v185
	v_add_f32_e32 v186, 1.0, v186
	v_add_f32_e32 v187, 1.0, v187
	v_add_f32_e32 v188, 1.0, v188
	v_add_f32_e32 v189, 1.0, v189
	v_add_f32_e32 v190, 1.0, v190
	v_add_f32_e32 v191, 1.0, v191
	v_rcp_f32_e32 v156, v156
	v_rcp_f32_e32 v157, v157
	v_rcp_f32_e32 v158, v158
	v_rcp_f32_e32 v159, v159
	v_rcp_f32_e32 v160, v160
	v_rcp_f32_e32 v161, v161
	v_rcp_f32_e32 v162, v162
	v_rcp_f32_e32 v163, v163
	v_rcp_f32_e32 v184, v184
	v_rcp_f32_e32 v185, v185
	v_rcp_f32_e32 v186, v186
	v_rcp_f32_e32 v187, v187
	v_rcp_f32_e32 v188, v188
	v_rcp_f32_e32 v189, v189
	v_rcp_f32_e32 v190, v190
	v_rcp_f32_e32 v191, v191
	v_sub_f32_e32 v128, 1.0, v156
	v_sub_f32_e32 v129, 1.0, v157
	v_sub_f32_e32 v130, 1.0, v158
	v_sub_f32_e32 v131, 1.0, v159
	v_sub_f32_e32 v132, 1.0, v160
	v_sub_f32_e32 v133, 1.0, v161
	v_sub_f32_e32 v134, 1.0, v162
	v_sub_f32_e32 v135, 1.0, v163
	v_sub_f32_e32 v164, 1.0, v184
	v_sub_f32_e32 v165, 1.0, v185
	v_sub_f32_e32 v166, 1.0, v186
	v_sub_f32_e32 v167, 1.0, v187
	v_sub_f32_e32 v180, 1.0, v188
	v_sub_f32_e32 v181, 1.0, v189
	v_sub_f32_e32 v182, 1.0, v190
	v_sub_f32_e32 v183, 1.0, v191
	s_lshr_b32 s44, s3, 6
	s_mov_b32 s3, 16
	s_cmp_eq_u32 s44, 1
	s_cbranch_scc1 .Lseg5_g2
	s_cmp_eq_u32 s44, 2
	s_cbranch_scc1 .Lseg5_g4
	s_cmp_eq_u32 s44, 3
	s_cbranch_scc1 .Lseg5_g6
	s_cmp_eq_u32 s44, 4
	s_cbranch_scc1 .Lseg5_g8
	s_cmp_eq_u32 s44, 5
	s_cbranch_scc1 .Lseg5_g10
	s_cmp_eq_u32 s44, 6
	s_cbranch_scc1 .Lseg5_g12
	s_cmp_eq_u32 s44, 7
	s_cbranch_scc1 .Lseg5_g14
; __device__ __forceinline__ unsigned cvt_pk_bf16(float lo, float hi) { f32x2_t v = {lo, hi}; bf16x2_t b = __builtin_convertvector(v, bf16x2_t); return __builtin_bit_cast(unsigned, b); }
; __device__ __forceinline__ float sigmoidf_(float v) { return __builtin_amdgcn_rcpf(1.f + __expf(-v)); }
;     __device__ __forceinline__ void operator()(const f32x4 (&acc)[2][2][4][2], const pg8::Unit& u, int wr, int wc, int fr, int fq) const {
;     ...
;                     for (int m = 0; m < 4; ++m) {
;                         bf16_t* p = (bf16_t*)G + (size_t)(row0 + ai * 128 + m * 16) * 1024 + col;
;                         f32x4 a = acc[ai][bj][m][0], b = acc[ai][bj][m][1], ga, gb;
; #pragma unroll
;                         for (int j = 0; j < 4; ++j) { ga[j] = __logf(lb[j] + (1.f - lb[j]) * sigmoidf_(a[j])); gb[j] = __logf(lb[4 + j] + (1.f - lb[4 + j]) * sigmoidf_(b[j])); }
;                         u32x4 w; w.x = cvt_pk_bf16(ga[0], ga[1]); w.y = cvt_pk_bf16(ga[2], ga[3]); w.z = cvt_pk_bf16(gb[0], gb[1]); w.w = cvt_pk_bf16(gb[2], gb[3]);
;                         *(u32x4*)p = w;
.Lseg5_g0:
	v_mul_f32_e32 v124, s98, v124
	v_mul_f32_e32 v125, s98, v125
	v_mul_f32_e32 v126, s98, v126
	v_mul_f32_e32 v127, s98, v127
	v_mul_f32_e32 v120, s98, v120
	v_mul_f32_e32 v121, s98, v121
	v_mul_f32_e32 v122, s98, v122
	v_mul_f32_e32 v123, s98, v123
	v_exp_f32_e32 v124, v124
	v_exp_f32_e32 v125, v125
	v_exp_f32_e32 v126, v126
	v_exp_f32_e32 v127, v127
	v_exp_f32_e32 v120, v120
	v_exp_f32_e32 v121, v121
	v_exp_f32_e32 v122, v122
	v_exp_f32_e32 v123, v123
	v_add_f32_e32 v124, 1.0, v124
	v_add_f32_e32 v125, 1.0, v125
	v_add_f32_e32 v126, 1.0, v126
	v_add_f32_e32 v127, 1.0, v127
	v_add_f32_e32 v120, 1.0, v120
	v_add_f32_e32 v121, 1.0, v121
	v_add_f32_e32 v122, 1.0, v122
	v_add_f32_e32 v123, 1.0, v123
	v_rcp_f32_e32 v124, v124
	v_rcp_f32_e32 v125, v125
	v_rcp_f32_e32 v126, v126
	v_rcp_f32_e32 v127, v127
	v_rcp_f32_e32 v120, v120
	v_rcp_f32_e32 v121, v121
	v_rcp_f32_e32 v122, v122
	v_rcp_f32_e32 v123, v123
	v_fma_f32 v124, v124, v128, v156
	v_fma_f32 v125, v125, v129, v157
	v_fma_f32 v126, v126, v130, v158
	v_fma_f32 v127, v127, v131, v159
	v_fma_f32 v120, v120, v132, v160
	v_fma_f32 v121, v121, v133, v161
	v_fma_f32 v122, v122, v134, v162
	v_fma_f32 v123, v123, v135, v163
	v_cmp_gt_f32_e64 vcc, s12, v124
	v_cmp_gt_f32_e64 s[44:45], s12, v125
	v_cmp_gt_f32_e64 s[46:47], s12, v126
	v_cmp_gt_f32_e64 s[48:49], s12, v127
	v_cndmask_b32_e64 v192, 0, 32, vcc
	v_cndmask_b32_e64 v193, 0, 32, s[44:45]
	v_cndmask_b32_e64 v194, 0, 32, s[46:47]
	v_cndmask_b32_e64 v195, 0, 32, s[48:49]
	v_ldexp_f32 v124, v124, v192
	v_ldexp_f32 v125, v125, v193
	v_ldexp_f32 v126, v126, v194
	v_ldexp_f32 v127, v127, v195
	v_log_f32_e32 v124, v124
	v_log_f32_e32 v125, v125
	v_log_f32_e32 v126, v126
	v_log_f32_e32 v127, v127
	v_mul_f32_e32 v192, s13, v124
	v_mul_f32_e32 v193, s13, v125
	v_mul_f32_e32 v194, s13, v126
	v_mul_f32_e32 v195, s13, v127
	v_fma_f32 v192, v124, s13, -v192
	v_fma_f32 v193, v125, s13, -v193
	v_fma_f32 v194, v126, s13, -v194
	v_fma_f32 v195, v127, s13, -v195
	v_fmac_f32_e32 v192, s99, v124
	v_fmac_f32_e32 v193, s99, v125
	v_fmac_f32_e32 v194, s99, v126
	v_fmac_f32_e32 v195, s99, v127
	v_fmac_f32_e32 v192, s13, v124
	v_fmac_f32_e32 v193, s13, v125
	v_fmac_f32_e32 v194, s13, v126
	v_fmac_f32_e32 v195, s13, v127
	v_cmp_lt_f32_e64 s[4:5], |v124|, s20
	v_cmp_lt_f32_e64 s[50:51], |v125|, s20
	v_cmp_lt_f32_e64 s[54:55], |v126|, s20
	v_cmp_lt_f32_e64 s[56:57], |v127|, s20
	v_cndmask_b32_e64 v124, v124, v192, s[4:5]
	v_cndmask_b32_e64 v125, v125, v193, s[50:51]
	v_cndmask_b32_e64 v126, v126, v194, s[54:55]
	v_cndmask_b32_e64 v127, v127, v195, s[56:57]
	v_cndmask_b32_e64 v192, 0, v177, vcc
	v_cndmask_b32_e64 v193, 0, v177, s[44:45]
	v_cndmask_b32_e64 v194, 0, v177, s[46:47]
	v_cndmask_b32_e64 v195, 0, v177, s[48:49]
	v_sub_f32_e32 v124, v124, v192
	v_sub_f32_e32 v125, v125, v193
	v_sub_f32_e32 v126, v126, v194
	v_sub_f32_e32 v127, v127, v195
	v_cmp_gt_f32_e64 vcc, s12, v120
	v_cmp_gt_f32_e64 s[44:45], s12, v121
	v_cmp_gt_f32_e64 s[46:47], s12, v122
	v_cmp_gt_f32_e64 s[48:49], s12, v123
	v_cndmask_b32_e64 v196, 0, 32, vcc
	v_cndmask_b32_e64 v197, 0, 32, s[44:45]
	v_cndmask_b32_e64 v198, 0, 32, s[46:47]
	v_cndmask_b32_e64 v199, 0, 32, s[48:49]
	v_ldexp_f32 v120, v120, v196
	v_ldexp_f32 v121, v121, v197
	v_ldexp_f32 v122, v122, v198
	v_ldexp_f32 v123, v123, v199
	v_log_f32_e32 v120, v120
	v_log_f32_e32 v121, v121
	v_log_f32_e32 v122, v122
	v_log_f32_e32 v123, v123
	v_mul_f32_e32 v196, s13, v120
	v_mul_f32_e32 v197, s13, v121
	v_mul_f32_e32 v198, s13, v122
	v_mul_f32_e32 v199, s13, v123
	v_fma_f32 v196, v120, s13, -v196
	v_fma_f32 v197, v121, s13, -v197
	v_fma_f32 v198, v122, s13, -v198
	v_fma_f32 v199, v123, s13, -v199
	v_fmac_f32_e32 v196, s99, v120
	v_fmac_f32_e32 v197, s99, v121
	v_fmac_f32_e32 v198, s99, v122
	v_fmac_f32_e32 v199, s99, v123
	v_fmac_f32_e32 v196, s13, v120
	v_fmac_f32_e32 v197, s13, v121
	v_fmac_f32_e32 v198, s13, v122
	v_fmac_f32_e32 v199, s13, v123
	v_cmp_lt_f32_e64 s[4:5], |v120|, s20
	v_cmp_lt_f32_e64 s[50:51], |v121|, s20
	v_cmp_lt_f32_e64 s[54:55], |v122|, s20
	v_cmp_lt_f32_e64 s[56:57], |v123|, s20
	v_cndmask_b32_e64 v120, v120, v196, s[4:5]
	v_cndmask_b32_e64 v121, v121, v197, s[50:51]
	v_cndmask_b32_e64 v122, v122, v198, s[54:55]
	v_cndmask_b32_e64 v123, v123, v199, s[56:57]
	v_cndmask_b32_e64 v196, 0, v177, vcc
	v_cndmask_b32_e64 v197, 0, v177, s[44:45]
	v_cndmask_b32_e64 v198, 0, v177, s[46:47]
	v_cndmask_b32_e64 v199, 0, v177, s[48:49]
	v_sub_f32_e32 v120, v120, v196
	v_sub_f32_e32 v121, v121, v197
	v_sub_f32_e32 v122, v122, v198
	v_sub_f32_e32 v123, v123, v199
	v_cvt_pk_bf16_f32 v124, v124, v125
	v_cvt_pk_bf16_f32 v125, v126, v127
	v_cvt_pk_bf16_f32 v126, v120, v121
	v_cvt_pk_bf16_f32 v127, v122, v123
	v_mov_b32_e32 v144, v179
	global_store_dwordx4 v144, v[124:127], s[64:65]
	s_add_i32 s3, s3, -1
	s_cmp_eq_u32 s3, 0
	s_cbranch_scc1 .Lseg5_done
; __device__ __forceinline__ unsigned cvt_pk_bf16(float lo, float hi) { f32x2_t v = {lo, hi}; bf16x2_t b = __builtin_convertvector(v, bf16x2_t); return __builtin_bit_cast(unsigned, b); }
; __device__ __forceinline__ float sigmoidf_(float v) { return __builtin_amdgcn_rcpf(1.f + __expf(-v)); }
;     __device__ __forceinline__ void operator()(const f32x4 (&acc)[2][2][4][2], const pg8::Unit& u, int wr, int wc, int fr, int fq) const {
;     ...
;                     for (int m = 0; m < 4; ++m) {
;                         bf16_t* p = (bf16_t*)G + (size_t)(row0 + ai * 128 + m * 16) * 1024 + col;
;                         f32x4 a = acc[ai][bj][m][0], b = acc[ai][bj][m][1], ga, gb;
; #pragma unroll
;                         for (int j = 0; j < 4; ++j) { ga[j] = __logf(lb[j] + (1.f - lb[j]) * sigmoidf_(a[j])); gb[j] = __logf(lb[4 + j] + (1.f - lb[4 + j]) * sigmoidf_(b[j])); }
;                         u32x4 w; w.x = cvt_pk_bf16(ga[0], ga[1]); w.y = cvt_pk_bf16(ga[2], ga[3]); w.z = cvt_pk_bf16(gb[0], gb[1]); w.w = cvt_pk_bf16(gb[2], gb[3]);
;                         *(u32x4*)p = w;
.Lseg5_g1:
	v_mul_f32_e32 v112, s98, v112
	v_mul_f32_e32 v113, s98, v113
	v_mul_f32_e32 v114, s98, v114
	v_mul_f32_e32 v115, s98, v115
	v_mul_f32_e32 v104, s98, v104
	v_mul_f32_e32 v105, s98, v105
	v_mul_f32_e32 v106, s98, v106
	v_mul_f32_e32 v107, s98, v107
	v_exp_f32_e32 v112, v112
	v_exp_f32_e32 v113, v113
	v_exp_f32_e32 v114, v114
	v_exp_f32_e32 v115, v115
	v_exp_f32_e32 v104, v104
	v_exp_f32_e32 v105, v105
	v_exp_f32_e32 v106, v106
	v_exp_f32_e32 v107, v107
	v_add_f32_e32 v112, 1.0, v112
	v_add_f32_e32 v113, 1.0, v113
	v_add_f32_e32 v114, 1.0, v114
	v_add_f32_e32 v115, 1.0, v115
	v_add_f32_e32 v104, 1.0, v104
	v_add_f32_e32 v105, 1.0, v105
	v_add_f32_e32 v106, 1.0, v106
	v_add_f32_e32 v107, 1.0, v107
	v_rcp_f32_e32 v112, v112
	v_rcp_f32_e32 v113, v113
	v_rcp_f32_e32 v114, v114
	v_rcp_f32_e32 v115, v115
	v_rcp_f32_e32 v104, v104
	v_rcp_f32_e32 v105, v105
	v_rcp_f32_e32 v106, v106
	v_rcp_f32_e32 v107, v107
	v_fma_f32 v112, v112, v128, v156
	v_fma_f32 v113, v113, v129, v157
	v_fma_f32 v114, v114, v130, v158
	v_fma_f32 v115, v115, v131, v159
	v_fma_f32 v104, v104, v132, v160
	v_fma_f32 v105, v105, v133, v161
	v_fma_f32 v106, v106, v134, v162
	v_fma_f32 v107, v107, v135, v163
	v_cmp_gt_f32_e64 vcc, s12, v112
	v_cmp_gt_f32_e64 s[44:45], s12, v113
	v_cmp_gt_f32_e64 s[46:47], s12, v114
	v_cmp_gt_f32_e64 s[48:49], s12, v115
	v_cndmask_b32_e64 v192, 0, 32, vcc
	v_cndmask_b32_e64 v193, 0, 32, s[44:45]
	v_cndmask_b32_e64 v194, 0, 32, s[46:47]
	v_cndmask_b32_e64 v195, 0, 32, s[48:49]
	v_ldexp_f32 v112, v112, v192
	v_ldexp_f32 v113, v113, v193
	v_ldexp_f32 v114, v114, v194
	v_ldexp_f32 v115, v115, v195
	v_log_f32_e32 v112, v112
	v_log_f32_e32 v113, v113
	v_log_f32_e32 v114, v114
	v_log_f32_e32 v115, v115
	v_mul_f32_e32 v192, s13, v112
	v_mul_f32_e32 v193, s13, v113
	v_mul_f32_e32 v194, s13, v114
	v_mul_f32_e32 v195, s13, v115
	v_fma_f32 v192, v112, s13, -v192
	v_fma_f32 v193, v113, s13, -v193
	v_fma_f32 v194, v114, s13, -v194
	v_fma_f32 v195, v115, s13, -v195
	v_fmac_f32_e32 v192, s99, v112
	v_fmac_f32_e32 v193, s99, v113
	v_fmac_f32_e32 v194, s99, v114
	v_fmac_f32_e32 v195, s99, v115
	v_fmac_f32_e32 v192, s13, v112
	v_fmac_f32_e32 v193, s13, v113
	v_fmac_f32_e32 v194, s13, v114
	v_fmac_f32_e32 v195, s13, v115
	v_cmp_lt_f32_e64 s[4:5], |v112|, s20
	v_cmp_lt_f32_e64 s[50:51], |v113|, s20
	v_cmp_lt_f32_e64 s[54:55], |v114|, s20
	v_cmp_lt_f32_e64 s[56:57], |v115|, s20
	v_cndmask_b32_e64 v112, v112, v192, s[4:5]
	v_cndmask_b32_e64 v113, v113, v193, s[50:51]
	v_cndmask_b32_e64 v114, v114, v194, s[54:55]
	v_cndmask_b32_e64 v115, v115, v195, s[56:57]
	v_cndmask_b32_e64 v192, 0, v177, vcc
	v_cndmask_b32_e64 v193, 0, v177, s[44:45]
	v_cndmask_b32_e64 v194, 0, v177, s[46:47]
	v_cndmask_b32_e64 v195, 0, v177, s[48:49]
	v_sub_f32_e32 v112, v112, v192
	v_sub_f32_e32 v113, v113, v193
	v_sub_f32_e32 v114, v114, v194
	v_sub_f32_e32 v115, v115, v195
	v_cmp_gt_f32_e64 vcc, s12, v104
	v_cmp_gt_f32_e64 s[44:45], s12, v105
	v_cmp_gt_f32_e64 s[46:47], s12, v106
	v_cmp_gt_f32_e64 s[48:49], s12, v107
	v_cndmask_b32_e64 v196, 0, 32, vcc
	v_cndmask_b32_e64 v197, 0, 32, s[44:45]
	v_cndmask_b32_e64 v198, 0, 32, s[46:47]
	v_cndmask_b32_e64 v199, 0, 32, s[48:49]
	v_ldexp_f32 v104, v104, v196
	v_ldexp_f32 v105, v105, v197
	v_ldexp_f32 v106, v106, v198
	v_ldexp_f32 v107, v107, v199
	v_log_f32_e32 v104, v104
	v_log_f32_e32 v105, v105
	v_log_f32_e32 v106, v106
	v_log_f32_e32 v107, v107
	v_mul_f32_e32 v196, s13, v104
	v_mul_f32_e32 v197, s13, v105
	v_mul_f32_e32 v198, s13, v106
	v_mul_f32_e32 v199, s13, v107
	v_fma_f32 v196, v104, s13, -v196
	v_fma_f32 v197, v105, s13, -v197
	v_fma_f32 v198, v106, s13, -v198
	v_fma_f32 v199, v107, s13, -v199
	v_fmac_f32_e32 v196, s99, v104
	v_fmac_f32_e32 v197, s99, v105
	v_fmac_f32_e32 v198, s99, v106
	v_fmac_f32_e32 v199, s99, v107
	v_fmac_f32_e32 v196, s13, v104
	v_fmac_f32_e32 v197, s13, v105
	v_fmac_f32_e32 v198, s13, v106
	v_fmac_f32_e32 v199, s13, v107
	v_cmp_lt_f32_e64 s[4:5], |v104|, s20
	v_cmp_lt_f32_e64 s[50:51], |v105|, s20
	v_cmp_lt_f32_e64 s[54:55], |v106|, s20
	v_cmp_lt_f32_e64 s[56:57], |v107|, s20
	v_cndmask_b32_e64 v104, v104, v196, s[4:5]
	v_cndmask_b32_e64 v105, v105, v197, s[50:51]
	v_cndmask_b32_e64 v106, v106, v198, s[54:55]
	v_cndmask_b32_e64 v107, v107, v199, s[56:57]
	v_cndmask_b32_e64 v196, 0, v177, vcc
	v_cndmask_b32_e64 v197, 0, v177, s[44:45]
	v_cndmask_b32_e64 v198, 0, v177, s[46:47]
	v_cndmask_b32_e64 v199, 0, v177, s[48:49]
	v_sub_f32_e32 v104, v104, v196
	v_sub_f32_e32 v105, v105, v197
	v_sub_f32_e32 v106, v106, v198
	v_sub_f32_e32 v107, v107, v199
	v_cvt_pk_bf16_f32 v112, v112, v113
	v_cvt_pk_bf16_f32 v113, v114, v115
	v_cvt_pk_bf16_f32 v114, v104, v105
	v_cvt_pk_bf16_f32 v115, v106, v107
	v_add_u32_e32 v155, 0x8000, v179
	global_store_dwordx4 v155, v[112:115], s[64:65]
	s_add_i32 s3, s3, -1
	s_cmp_eq_u32 s3, 0
	s_cbranch_scc1 .Lseg5_done
; __device__ __forceinline__ unsigned cvt_pk_bf16(float lo, float hi) { f32x2_t v = {lo, hi}; bf16x2_t b = __builtin_convertvector(v, bf16x2_t); return __builtin_bit_cast(unsigned, b); }
; __device__ __forceinline__ float sigmoidf_(float v) { return __builtin_amdgcn_rcpf(1.f + __expf(-v)); }
;     __device__ __forceinline__ void operator()(const f32x4 (&acc)[2][2][4][2], const pg8::Unit& u, int wr, int wc, int fr, int fq) const {
;     ...
;                     for (int m = 0; m < 4; ++m) {
;                         bf16_t* p = (bf16_t*)G + (size_t)(row0 + ai * 128 + m * 16) * 1024 + col;
;                         f32x4 a = acc[ai][bj][m][0], b = acc[ai][bj][m][1], ga, gb;
; #pragma unroll
;                         for (int j = 0; j < 4; ++j) { ga[j] = __logf(lb[j] + (1.f - lb[j]) * sigmoidf_(a[j])); gb[j] = __logf(lb[4 + j] + (1.f - lb[4 + j]) * sigmoidf_(b[j])); }
;                         u32x4 w; w.x = cvt_pk_bf16(ga[0], ga[1]); w.y = cvt_pk_bf16(ga[2], ga[3]); w.z = cvt_pk_bf16(gb[0], gb[1]); w.w = cvt_pk_bf16(gb[2], gb[3]);
;                         *(u32x4*)p = w;
.Lseg5_g2:
	v_mul_f32_e32 v100, s98, v100
	v_mul_f32_e32 v101, s98, v101
	v_mul_f32_e32 v102, s98, v102
	v_mul_f32_e32 v103, s98, v103
	v_mul_f32_e32 v92, s98, v92
	v_mul_f32_e32 v93, s98, v93
	v_mul_f32_e32 v94, s98, v94
	v_mul_f32_e32 v95, s98, v95
	v_exp_f32_e32 v100, v100
	v_exp_f32_e32 v101, v101
	v_exp_f32_e32 v102, v102
	v_exp_f32_e32 v103, v103
	v_exp_f32_e32 v92, v92
	v_exp_f32_e32 v93, v93
	v_exp_f32_e32 v94, v94
	v_exp_f32_e32 v95, v95
	v_add_f32_e32 v100, 1.0, v100
	v_add_f32_e32 v101, 1.0, v101
	v_add_f32_e32 v102, 1.0, v102
	v_add_f32_e32 v103, 1.0, v103
	v_add_f32_e32 v92, 1.0, v92
	v_add_f32_e32 v93, 1.0, v93
	v_add_f32_e32 v94, 1.0, v94
	v_add_f32_e32 v95, 1.0, v95
	v_rcp_f32_e32 v100, v100
	v_rcp_f32_e32 v101, v101
	v_rcp_f32_e32 v102, v102
	v_rcp_f32_e32 v103, v103
	v_rcp_f32_e32 v92, v92
	v_rcp_f32_e32 v93, v93
	v_rcp_f32_e32 v94, v94
	v_rcp_f32_e32 v95, v95
	v_fma_f32 v100, v100, v128, v156
	v_fma_f32 v101, v101, v129, v157
	v_fma_f32 v102, v102, v130, v158
	v_fma_f32 v103, v103, v131, v159
	v_fma_f32 v92, v92, v132, v160
	v_fma_f32 v93, v93, v133, v161
	v_fma_f32 v94, v94, v134, v162
	v_fma_f32 v95, v95, v135, v163
	v_cmp_gt_f32_e64 vcc, s12, v100
	v_cmp_gt_f32_e64 s[44:45], s12, v101
	v_cmp_gt_f32_e64 s[46:47], s12, v102
	v_cmp_gt_f32_e64 s[48:49], s12, v103
	v_cndmask_b32_e64 v192, 0, 32, vcc
	v_cndmask_b32_e64 v193, 0, 32, s[44:45]
	v_cndmask_b32_e64 v194, 0, 32, s[46:47]
	v_cndmask_b32_e64 v195, 0, 32, s[48:49]
	v_ldexp_f32 v100, v100, v192
	v_ldexp_f32 v101, v101, v193
	v_ldexp_f32 v102, v102, v194
	v_ldexp_f32 v103, v103, v195
	v_log_f32_e32 v100, v100
	v_log_f32_e32 v101, v101
	v_log_f32_e32 v102, v102
	v_log_f32_e32 v103, v103
	v_mul_f32_e32 v192, s13, v100
	v_mul_f32_e32 v193, s13, v101
	v_mul_f32_e32 v194, s13, v102
	v_mul_f32_e32 v195, s13, v103
	v_fma_f32 v192, v100, s13, -v192
	v_fma_f32 v193, v101, s13, -v193
	v_fma_f32 v194, v102, s13, -v194
	v_fma_f32 v195, v103, s13, -v195
	v_fmac_f32_e32 v192, s99, v100
	v_fmac_f32_e32 v193, s99, v101
	v_fmac_f32_e32 v194, s99, v102
	v_fmac_f32_e32 v195, s99, v103
	v_fmac_f32_e32 v192, s13, v100
	v_fmac_f32_e32 v193, s13, v101
	v_fmac_f32_e32 v194, s13, v102
	v_fmac_f32_e32 v195, s13, v103
	v_cmp_lt_f32_e64 s[4:5], |v100|, s20
	v_cmp_lt_f32_e64 s[50:51], |v101|, s20
	v_cmp_lt_f32_e64 s[54:55], |v102|, s20
	v_cmp_lt_f32_e64 s[56:57], |v103|, s20
	v_cndmask_b32_e64 v100, v100, v192, s[4:5]
	v_cndmask_b32_e64 v101, v101, v193, s[50:51]
	v_cndmask_b32_e64 v102, v102, v194, s[54:55]
	v_cndmask_b32_e64 v103, v103, v195, s[56:57]
	v_cndmask_b32_e64 v192, 0, v177, vcc
	v_cndmask_b32_e64 v193, 0, v177, s[44:45]
	v_cndmask_b32_e64 v194, 0, v177, s[46:47]
	v_cndmask_b32_e64 v195, 0, v177, s[48:49]
	v_sub_f32_e32 v100, v100, v192
	v_sub_f32_e32 v101, v101, v193
	v_sub_f32_e32 v102, v102, v194
	v_sub_f32_e32 v103, v103, v195
	v_cmp_gt_f32_e64 vcc, s12, v92
	v_cmp_gt_f32_e64 s[44:45], s12, v93
	v_cmp_gt_f32_e64 s[46:47], s12, v94
	v_cmp_gt_f32_e64 s[48:49], s12, v95
	v_cndmask_b32_e64 v196, 0, 32, vcc
	v_cndmask_b32_e64 v197, 0, 32, s[44:45]
	v_cndmask_b32_e64 v198, 0, 32, s[46:47]
	v_cndmask_b32_e64 v199, 0, 32, s[48:49]
	v_ldexp_f32 v92, v92, v196
	v_ldexp_f32 v93, v93, v197
	v_ldexp_f32 v94, v94, v198
	v_ldexp_f32 v95, v95, v199
	v_log_f32_e32 v92, v92
	v_log_f32_e32 v93, v93
	v_log_f32_e32 v94, v94
	v_log_f32_e32 v95, v95
	v_mul_f32_e32 v196, s13, v92
	v_mul_f32_e32 v197, s13, v93
	v_mul_f32_e32 v198, s13, v94
	v_mul_f32_e32 v199, s13, v95
	v_fma_f32 v196, v92, s13, -v196
	v_fma_f32 v197, v93, s13, -v197
	v_fma_f32 v198, v94, s13, -v198
	v_fma_f32 v199, v95, s13, -v199
	v_fmac_f32_e32 v196, s99, v92
	v_fmac_f32_e32 v197, s99, v93
	v_fmac_f32_e32 v198, s99, v94
	v_fmac_f32_e32 v199, s99, v95
	v_fmac_f32_e32 v196, s13, v92
	v_fmac_f32_e32 v197, s13, v93
	v_fmac_f32_e32 v198, s13, v94
	v_fmac_f32_e32 v199, s13, v95
	v_cmp_lt_f32_e64 s[4:5], |v92|, s20
	v_cmp_lt_f32_e64 s[50:51], |v93|, s20
	v_cmp_lt_f32_e64 s[54:55], |v94|, s20
	v_cmp_lt_f32_e64 s[56:57], |v95|, s20
	v_cndmask_b32_e64 v92, v92, v196, s[4:5]
	v_cndmask_b32_e64 v93, v93, v197, s[50:51]
	v_cndmask_b32_e64 v94, v94, v198, s[54:55]
	v_cndmask_b32_e64 v95, v95, v199, s[56:57]
	v_cndmask_b32_e64 v196, 0, v177, vcc
	v_cndmask_b32_e64 v197, 0, v177, s[44:45]
	v_cndmask_b32_e64 v198, 0, v177, s[46:47]
	v_cndmask_b32_e64 v199, 0, v177, s[48:49]
	v_sub_f32_e32 v92, v92, v196
	v_sub_f32_e32 v93, v93, v197
	v_sub_f32_e32 v94, v94, v198
	v_sub_f32_e32 v95, v95, v199
	v_cvt_pk_bf16_f32 v100, v100, v101
	v_cvt_pk_bf16_f32 v101, v102, v103
	v_cvt_pk_bf16_f32 v102, v92, v93
	v_cvt_pk_bf16_f32 v103, v94, v95
	v_add_u32_e32 v144, 0x10000, v179
	global_store_dwordx4 v144, v[100:103], s[64:65]
	s_add_i32 s3, s3, -1
	s_cmp_eq_u32 s3, 0
	s_cbranch_scc1 .Lseg5_done
; __device__ __forceinline__ unsigned cvt_pk_bf16(float lo, float hi) { f32x2_t v = {lo, hi}; bf16x2_t b = __builtin_convertvector(v, bf16x2_t); return __builtin_bit_cast(unsigned, b); }
; __device__ __forceinline__ float sigmoidf_(float v) { return __builtin_amdgcn_rcpf(1.f + __expf(-v)); }
;     __device__ __forceinline__ void operator()(const f32x4 (&acc)[2][2][4][2], const pg8::Unit& u, int wr, int wc, int fr, int fq) const {
;     ...
;                     for (int m = 0; m < 4; ++m) {
;                         bf16_t* p = (bf16_t*)G + (size_t)(row0 + ai * 128 + m * 16) * 1024 + col;
;                         f32x4 a = acc[ai][bj][m][0], b = acc[ai][bj][m][1], ga, gb;
; #pragma unroll
;                         for (int j = 0; j < 4; ++j) { ga[j] = __logf(lb[j] + (1.f - lb[j]) * sigmoidf_(a[j])); gb[j] = __logf(lb[4 + j] + (1.f - lb[4 + j]) * sigmoidf_(b[j])); }
;                         u32x4 w; w.x = cvt_pk_bf16(ga[0], ga[1]); w.y = cvt_pk_bf16(ga[2], ga[3]); w.z = cvt_pk_bf16(gb[0], gb[1]); w.w = cvt_pk_bf16(gb[2], gb[3]);
;                         *(u32x4*)p = w;
.Lseg5_g3:
	v_mul_f32_e32 v84, s98, v84
	v_mul_f32_e32 v85, s98, v85
	v_mul_f32_e32 v86, s98, v86
	v_mul_f32_e32 v87, s98, v87
	v_mul_f32_e32 v76, s98, v76
	v_mul_f32_e32 v77, s98, v77
	v_mul_f32_e32 v78, s98, v78
	v_mul_f32_e32 v79, s98, v79
	v_exp_f32_e32 v84, v84
	v_exp_f32_e32 v85, v85
	v_exp_f32_e32 v86, v86
	v_exp_f32_e32 v87, v87
	v_exp_f32_e32 v76, v76
	v_exp_f32_e32 v77, v77
	v_exp_f32_e32 v78, v78
	v_exp_f32_e32 v79, v79
	v_add_f32_e32 v84, 1.0, v84
	v_add_f32_e32 v85, 1.0, v85
	v_add_f32_e32 v86, 1.0, v86
	v_add_f32_e32 v87, 1.0, v87
	v_add_f32_e32 v76, 1.0, v76
	v_add_f32_e32 v77, 1.0, v77
	v_add_f32_e32 v78, 1.0, v78
	v_add_f32_e32 v79, 1.0, v79
	v_rcp_f32_e32 v84, v84
	v_rcp_f32_e32 v85, v85
	v_rcp_f32_e32 v86, v86
	v_rcp_f32_e32 v87, v87
	v_rcp_f32_e32 v76, v76
	v_rcp_f32_e32 v77, v77
	v_rcp_f32_e32 v78, v78
	v_rcp_f32_e32 v79, v79
	v_fma_f32 v84, v84, v128, v156
	v_fma_f32 v85, v85, v129, v157
	v_fma_f32 v86, v86, v130, v158
	v_fma_f32 v87, v87, v131, v159
	v_fma_f32 v76, v76, v132, v160
	v_fma_f32 v77, v77, v133, v161
	v_fma_f32 v78, v78, v134, v162
	v_fma_f32 v79, v79, v135, v163
	v_cmp_gt_f32_e64 vcc, s12, v84
	v_cmp_gt_f32_e64 s[44:45], s12, v85
	v_cmp_gt_f32_e64 s[46:47], s12, v86
	v_cmp_gt_f32_e64 s[48:49], s12, v87
	v_cndmask_b32_e64 v192, 0, 32, vcc
	v_cndmask_b32_e64 v193, 0, 32, s[44:45]
	v_cndmask_b32_e64 v194, 0, 32, s[46:47]
	v_cndmask_b32_e64 v195, 0, 32, s[48:49]
	v_ldexp_f32 v84, v84, v192
	v_ldexp_f32 v85, v85, v193
	v_ldexp_f32 v86, v86, v194
	v_ldexp_f32 v87, v87, v195
	v_log_f32_e32 v84, v84
	v_log_f32_e32 v85, v85
	v_log_f32_e32 v86, v86
	v_log_f32_e32 v87, v87
	v_mul_f32_e32 v192, s13, v84
	v_mul_f32_e32 v193, s13, v85
	v_mul_f32_e32 v194, s13, v86
	v_mul_f32_e32 v195, s13, v87
	v_fma_f32 v192, v84, s13, -v192
	v_fma_f32 v193, v85, s13, -v193
	v_fma_f32 v194, v86, s13, -v194
	v_fma_f32 v195, v87, s13, -v195
	v_fmac_f32_e32 v192, s99, v84
	v_fmac_f32_e32 v193, s99, v85
	v_fmac_f32_e32 v194, s99, v86
	v_fmac_f32_e32 v195, s99, v87
	v_fmac_f32_e32 v192, s13, v84
	v_fmac_f32_e32 v193, s13, v85
	v_fmac_f32_e32 v194, s13, v86
	v_fmac_f32_e32 v195, s13, v87
	v_cmp_lt_f32_e64 s[4:5], |v84|, s20
	v_cmp_lt_f32_e64 s[50:51], |v85|, s20
	v_cmp_lt_f32_e64 s[54:55], |v86|, s20
	v_cmp_lt_f32_e64 s[56:57], |v87|, s20
	v_cndmask_b32_e64 v84, v84, v192, s[4:5]
	v_cndmask_b32_e64 v85, v85, v193, s[50:51]
	v_cndmask_b32_e64 v86, v86, v194, s[54:55]
	v_cndmask_b32_e64 v87, v87, v195, s[56:57]
	v_cndmask_b32_e64 v192, 0, v177, vcc
	v_cndmask_b32_e64 v193, 0, v177, s[44:45]
	v_cndmask_b32_e64 v194, 0, v177, s[46:47]
	v_cndmask_b32_e64 v195, 0, v177, s[48:49]
	v_sub_f32_e32 v84, v84, v192
	v_sub_f32_e32 v85, v85, v193
	v_sub_f32_e32 v86, v86, v194
	v_sub_f32_e32 v87, v87, v195
	v_cmp_gt_f32_e64 vcc, s12, v76
	v_cmp_gt_f32_e64 s[44:45], s12, v77
	v_cmp_gt_f32_e64 s[46:47], s12, v78
	v_cmp_gt_f32_e64 s[48:49], s12, v79
	v_cndmask_b32_e64 v196, 0, 32, vcc
	v_cndmask_b32_e64 v197, 0, 32, s[44:45]
	v_cndmask_b32_e64 v198, 0, 32, s[46:47]
	v_cndmask_b32_e64 v199, 0, 32, s[48:49]
	v_ldexp_f32 v76, v76, v196
	v_ldexp_f32 v77, v77, v197
	v_ldexp_f32 v78, v78, v198
	v_ldexp_f32 v79, v79, v199
	v_log_f32_e32 v76, v76
	v_log_f32_e32 v77, v77
	v_log_f32_e32 v78, v78
	v_log_f32_e32 v79, v79
	v_mul_f32_e32 v196, s13, v76
	v_mul_f32_e32 v197, s13, v77
	v_mul_f32_e32 v198, s13, v78
	v_mul_f32_e32 v199, s13, v79
	v_fma_f32 v196, v76, s13, -v196
	v_fma_f32 v197, v77, s13, -v197
	v_fma_f32 v198, v78, s13, -v198
	v_fma_f32 v199, v79, s13, -v199
	v_fmac_f32_e32 v196, s99, v76
	v_fmac_f32_e32 v197, s99, v77
	v_fmac_f32_e32 v198, s99, v78
	v_fmac_f32_e32 v199, s99, v79
	v_fmac_f32_e32 v196, s13, v76
	v_fmac_f32_e32 v197, s13, v77
	v_fmac_f32_e32 v198, s13, v78
	v_fmac_f32_e32 v199, s13, v79
	v_cmp_lt_f32_e64 s[4:5], |v76|, s20
	v_cmp_lt_f32_e64 s[50:51], |v77|, s20
	v_cmp_lt_f32_e64 s[54:55], |v78|, s20
	v_cmp_lt_f32_e64 s[56:57], |v79|, s20
	v_cndmask_b32_e64 v76, v76, v196, s[4:5]
	v_cndmask_b32_e64 v77, v77, v197, s[50:51]
	v_cndmask_b32_e64 v78, v78, v198, s[54:55]
	v_cndmask_b32_e64 v79, v79, v199, s[56:57]
	v_cndmask_b32_e64 v196, 0, v177, vcc
	v_cndmask_b32_e64 v197, 0, v177, s[44:45]
	v_cndmask_b32_e64 v198, 0, v177, s[46:47]
	v_cndmask_b32_e64 v199, 0, v177, s[48:49]
	v_sub_f32_e32 v76, v76, v196
	v_sub_f32_e32 v77, v77, v197
	v_sub_f32_e32 v78, v78, v198
	v_sub_f32_e32 v79, v79, v199
	v_cvt_pk_bf16_f32 v84, v84, v85
	v_cvt_pk_bf16_f32 v85, v86, v87
	v_cvt_pk_bf16_f32 v86, v76, v77
	v_cvt_pk_bf16_f32 v87, v78, v79
	v_add_u32_e32 v155, 0x18000, v179
	global_store_dwordx4 v155, v[84:87], s[64:65]
	s_add_i32 s3, s3, -1
	s_cmp_eq_u32 s3, 0
	s_cbranch_scc1 .Lseg5_done
; __device__ __forceinline__ unsigned cvt_pk_bf16(float lo, float hi) { f32x2_t v = {lo, hi}; bf16x2_t b = __builtin_convertvector(v, bf16x2_t); return __builtin_bit_cast(unsigned, b); }
; __device__ __forceinline__ float sigmoidf_(float v) { return __builtin_amdgcn_rcpf(1.f + __expf(-v)); }
;     __device__ __forceinline__ void operator()(const f32x4 (&acc)[2][2][4][2], const pg8::Unit& u, int wr, int wc, int fr, int fq) const {
;     ...
;                     for (int m = 0; m < 4; ++m) {
;                         bf16_t* p = (bf16_t*)G + (size_t)(row0 + ai * 128 + m * 16) * 1024 + col;
;                         f32x4 a = acc[ai][bj][m][0], b = acc[ai][bj][m][1], ga, gb;
; #pragma unroll
;                         for (int j = 0; j < 4; ++j) { ga[j] = __logf(lb[j] + (1.f - lb[j]) * sigmoidf_(a[j])); gb[j] = __logf(lb[4 + j] + (1.f - lb[4 + j]) * sigmoidf_(b[j])); }
;                         u32x4 w; w.x = cvt_pk_bf16(ga[0], ga[1]); w.y = cvt_pk_bf16(ga[2], ga[3]); w.z = cvt_pk_bf16(gb[0], gb[1]); w.w = cvt_pk_bf16(gb[2], gb[3]);
;                         *(u32x4*)p = w;
.Lseg5_g4:
	v_mul_f32_e32 v60, s98, v60
	v_mul_f32_e32 v61, s98, v61
	v_mul_f32_e32 v62, s98, v62
	v_mul_f32_e32 v63, s98, v63
	v_mul_f32_e32 v56, s98, v56
	v_mul_f32_e32 v57, s98, v57
	v_mul_f32_e32 v58, s98, v58
	v_mul_f32_e32 v59, s98, v59
	v_exp_f32_e32 v60, v60
	v_exp_f32_e32 v61, v61
	v_exp_f32_e32 v62, v62
	v_exp_f32_e32 v63, v63
	v_exp_f32_e32 v56, v56
	v_exp_f32_e32 v57, v57
	v_exp_f32_e32 v58, v58
	v_exp_f32_e32 v59, v59
	v_add_f32_e32 v60, 1.0, v60
	v_add_f32_e32 v61, 1.0, v61
	v_add_f32_e32 v62, 1.0, v62
	v_add_f32_e32 v63, 1.0, v63
	v_add_f32_e32 v56, 1.0, v56
	v_add_f32_e32 v57, 1.0, v57
	v_add_f32_e32 v58, 1.0, v58
	v_add_f32_e32 v59, 1.0, v59
	v_rcp_f32_e32 v60, v60
	v_rcp_f32_e32 v61, v61
	v_rcp_f32_e32 v62, v62
	v_rcp_f32_e32 v63, v63
	v_rcp_f32_e32 v56, v56
	v_rcp_f32_e32 v57, v57
	v_rcp_f32_e32 v58, v58
	v_rcp_f32_e32 v59, v59
	v_fma_f32 v60, v60, v128, v156
	v_fma_f32 v61, v61, v129, v157
	v_fma_f32 v62, v62, v130, v158
	v_fma_f32 v63, v63, v131, v159
	v_fma_f32 v56, v56, v132, v160
	v_fma_f32 v57, v57, v133, v161
	v_fma_f32 v58, v58, v134, v162
	v_fma_f32 v59, v59, v135, v163
	v_cmp_gt_f32_e64 vcc, s12, v60
	v_cmp_gt_f32_e64 s[44:45], s12, v61
	v_cmp_gt_f32_e64 s[46:47], s12, v62
	v_cmp_gt_f32_e64 s[48:49], s12, v63
	v_cndmask_b32_e64 v192, 0, 32, vcc
	v_cndmask_b32_e64 v193, 0, 32, s[44:45]
	v_cndmask_b32_e64 v194, 0, 32, s[46:47]
	v_cndmask_b32_e64 v195, 0, 32, s[48:49]
	v_ldexp_f32 v60, v60, v192
	v_ldexp_f32 v61, v61, v193
	v_ldexp_f32 v62, v62, v194
	v_ldexp_f32 v63, v63, v195
	v_log_f32_e32 v60, v60
	v_log_f32_e32 v61, v61
	v_log_f32_e32 v62, v62
	v_log_f32_e32 v63, v63
	v_mul_f32_e32 v192, s13, v60
	v_mul_f32_e32 v193, s13, v61
	v_mul_f32_e32 v194, s13, v62
	v_mul_f32_e32 v195, s13, v63
	v_fma_f32 v192, v60, s13, -v192
	v_fma_f32 v193, v61, s13, -v193
	v_fma_f32 v194, v62, s13, -v194
	v_fma_f32 v195, v63, s13, -v195
	v_fmac_f32_e32 v192, s99, v60
	v_fmac_f32_e32 v193, s99, v61
	v_fmac_f32_e32 v194, s99, v62
	v_fmac_f32_e32 v195, s99, v63
	v_fmac_f32_e32 v192, s13, v60
	v_fmac_f32_e32 v193, s13, v61
	v_fmac_f32_e32 v194, s13, v62
	v_fmac_f32_e32 v195, s13, v63
	v_cmp_lt_f32_e64 s[4:5], |v60|, s20
	v_cmp_lt_f32_e64 s[50:51], |v61|, s20
	v_cmp_lt_f32_e64 s[54:55], |v62|, s20
	v_cmp_lt_f32_e64 s[56:57], |v63|, s20
	v_cndmask_b32_e64 v60, v60, v192, s[4:5]
	v_cndmask_b32_e64 v61, v61, v193, s[50:51]
	v_cndmask_b32_e64 v62, v62, v194, s[54:55]
	v_cndmask_b32_e64 v63, v63, v195, s[56:57]
	v_cndmask_b32_e64 v192, 0, v177, vcc
	v_cndmask_b32_e64 v193, 0, v177, s[44:45]
	v_cndmask_b32_e64 v194, 0, v177, s[46:47]
	v_cndmask_b32_e64 v195, 0, v177, s[48:49]
	v_sub_f32_e32 v60, v60, v192
	v_sub_f32_e32 v61, v61, v193
	v_sub_f32_e32 v62, v62, v194
	v_sub_f32_e32 v63, v63, v195
	v_cmp_gt_f32_e64 vcc, s12, v56
	v_cmp_gt_f32_e64 s[44:45], s12, v57
	v_cmp_gt_f32_e64 s[46:47], s12, v58
	v_cmp_gt_f32_e64 s[48:49], s12, v59
	v_cndmask_b32_e64 v196, 0, 32, vcc
	v_cndmask_b32_e64 v197, 0, 32, s[44:45]
	v_cndmask_b32_e64 v198, 0, 32, s[46:47]
	v_cndmask_b32_e64 v199, 0, 32, s[48:49]
	v_ldexp_f32 v56, v56, v196
	v_ldexp_f32 v57, v57, v197
	v_ldexp_f32 v58, v58, v198
	v_ldexp_f32 v59, v59, v199
	v_log_f32_e32 v56, v56
	v_log_f32_e32 v57, v57
	v_log_f32_e32 v58, v58
	v_log_f32_e32 v59, v59
	v_mul_f32_e32 v196, s13, v56
	v_mul_f32_e32 v197, s13, v57
	v_mul_f32_e32 v198, s13, v58
	v_mul_f32_e32 v199, s13, v59
	v_fma_f32 v196, v56, s13, -v196
	v_fma_f32 v197, v57, s13, -v197
	v_fma_f32 v198, v58, s13, -v198
	v_fma_f32 v199, v59, s13, -v199
	v_fmac_f32_e32 v196, s99, v56
	v_fmac_f32_e32 v197, s99, v57
	v_fmac_f32_e32 v198, s99, v58
	v_fmac_f32_e32 v199, s99, v59
	v_fmac_f32_e32 v196, s13, v56
	v_fmac_f32_e32 v197, s13, v57
	v_fmac_f32_e32 v198, s13, v58
	v_fmac_f32_e32 v199, s13, v59
	v_cmp_lt_f32_e64 s[4:5], |v56|, s20
	v_cmp_lt_f32_e64 s[50:51], |v57|, s20
	v_cmp_lt_f32_e64 s[54:55], |v58|, s20
	v_cmp_lt_f32_e64 s[56:57], |v59|, s20
	v_cndmask_b32_e64 v56, v56, v196, s[4:5]
	v_cndmask_b32_e64 v57, v57, v197, s[50:51]
	v_cndmask_b32_e64 v58, v58, v198, s[54:55]
	v_cndmask_b32_e64 v59, v59, v199, s[56:57]
	v_cndmask_b32_e64 v196, 0, v177, vcc
	v_cndmask_b32_e64 v197, 0, v177, s[44:45]
	v_cndmask_b32_e64 v198, 0, v177, s[46:47]
	v_cndmask_b32_e64 v199, 0, v177, s[48:49]
	v_sub_f32_e32 v56, v56, v196
	v_sub_f32_e32 v57, v57, v197
	v_sub_f32_e32 v58, v58, v198
	v_sub_f32_e32 v59, v59, v199
	v_cvt_pk_bf16_f32 v60, v60, v61
	v_cvt_pk_bf16_f32 v61, v62, v63
	v_cvt_pk_bf16_f32 v62, v56, v57
	v_cvt_pk_bf16_f32 v63, v58, v59
	v_add_u32_e32 v144, 0x40000, v179
	global_store_dwordx4 v144, v[60:63], s[64:65]
	s_add_i32 s3, s3, -1
	s_cmp_eq_u32 s3, 0
	s_cbranch_scc1 .Lseg5_done
; __device__ __forceinline__ unsigned cvt_pk_bf16(float lo, float hi) { f32x2_t v = {lo, hi}; bf16x2_t b = __builtin_convertvector(v, bf16x2_t); return __builtin_bit_cast(unsigned, b); }
; __device__ __forceinline__ float sigmoidf_(float v) { return __builtin_amdgcn_rcpf(1.f + __expf(-v)); }
;     __device__ __forceinline__ void operator()(const f32x4 (&acc)[2][2][4][2], const pg8::Unit& u, int wr, int wc, int fr, int fq) const {
;     ...
;                     for (int m = 0; m < 4; ++m) {
;                         bf16_t* p = (bf16_t*)G + (size_t)(row0 + ai * 128 + m * 16) * 1024 + col;
;                         f32x4 a = acc[ai][bj][m][0], b = acc[ai][bj][m][1], ga, gb;
; #pragma unroll
;                         for (int j = 0; j < 4; ++j) { ga[j] = __logf(lb[j] + (1.f - lb[j]) * sigmoidf_(a[j])); gb[j] = __logf(lb[4 + j] + (1.f - lb[4 + j]) * sigmoidf_(b[j])); }
;                         u32x4 w; w.x = cvt_pk_bf16(ga[0], ga[1]); w.y = cvt_pk_bf16(ga[2], ga[3]); w.z = cvt_pk_bf16(gb[0], gb[1]); w.w = cvt_pk_bf16(gb[2], gb[3]);
;                         *(u32x4*)p = w;
.Lseg5_g5:
	v_mul_f32_e32 v48, s98, v48
	v_mul_f32_e32 v49, s98, v49
	v_mul_f32_e32 v50, s98, v50
	v_mul_f32_e32 v51, s98, v51
	v_mul_f32_e32 v40, s98, v40
	v_mul_f32_e32 v41, s98, v41
	v_mul_f32_e32 v42, s98, v42
	v_mul_f32_e32 v43, s98, v43
	v_exp_f32_e32 v48, v48
	v_exp_f32_e32 v49, v49
	v_exp_f32_e32 v50, v50
	v_exp_f32_e32 v51, v51
	v_exp_f32_e32 v40, v40
	v_exp_f32_e32 v41, v41
	v_exp_f32_e32 v42, v42
	v_exp_f32_e32 v43, v43
	v_add_f32_e32 v48, 1.0, v48
	v_add_f32_e32 v49, 1.0, v49
	v_add_f32_e32 v50, 1.0, v50
	v_add_f32_e32 v51, 1.0, v51
	v_add_f32_e32 v40, 1.0, v40
	v_add_f32_e32 v41, 1.0, v41
	v_add_f32_e32 v42, 1.0, v42
	v_add_f32_e32 v43, 1.0, v43
	v_rcp_f32_e32 v48, v48
	v_rcp_f32_e32 v49, v49
	v_rcp_f32_e32 v50, v50
	v_rcp_f32_e32 v51, v51
	v_rcp_f32_e32 v40, v40
	v_rcp_f32_e32 v41, v41
	v_rcp_f32_e32 v42, v42
	v_rcp_f32_e32 v43, v43
	v_fma_f32 v48, v48, v128, v156
	v_fma_f32 v49, v49, v129, v157
	v_fma_f32 v50, v50, v130, v158
	v_fma_f32 v51, v51, v131, v159
	v_fma_f32 v40, v40, v132, v160
	v_fma_f32 v41, v41, v133, v161
	v_fma_f32 v42, v42, v134, v162
	v_fma_f32 v43, v43, v135, v163
	v_cmp_gt_f32_e64 vcc, s12, v48
	v_cmp_gt_f32_e64 s[44:45], s12, v49
	v_cmp_gt_f32_e64 s[46:47], s12, v50
	v_cmp_gt_f32_e64 s[48:49], s12, v51
	v_cndmask_b32_e64 v192, 0, 32, vcc
	v_cndmask_b32_e64 v193, 0, 32, s[44:45]
	v_cndmask_b32_e64 v194, 0, 32, s[46:47]
	v_cndmask_b32_e64 v195, 0, 32, s[48:49]
	v_ldexp_f32 v48, v48, v192
	v_ldexp_f32 v49, v49, v193
	v_ldexp_f32 v50, v50, v194
	v_ldexp_f32 v51, v51, v195
	v_log_f32_e32 v48, v48
	v_log_f32_e32 v49, v49
	v_log_f32_e32 v50, v50
	v_log_f32_e32 v51, v51
	v_mul_f32_e32 v192, s13, v48
	v_mul_f32_e32 v193, s13, v49
	v_mul_f32_e32 v194, s13, v50
	v_mul_f32_e32 v195, s13, v51
	v_fma_f32 v192, v48, s13, -v192
	v_fma_f32 v193, v49, s13, -v193
	v_fma_f32 v194, v50, s13, -v194
	v_fma_f32 v195, v51, s13, -v195
	v_fmac_f32_e32 v192, s99, v48
	v_fmac_f32_e32 v193, s99, v49
	v_fmac_f32_e32 v194, s99, v50
	v_fmac_f32_e32 v195, s99, v51
	v_fmac_f32_e32 v192, s13, v48
	v_fmac_f32_e32 v193, s13, v49
	v_fmac_f32_e32 v194, s13, v50
	v_fmac_f32_e32 v195, s13, v51
	v_cmp_lt_f32_e64 s[4:5], |v48|, s20
	v_cmp_lt_f32_e64 s[50:51], |v49|, s20
	v_cmp_lt_f32_e64 s[54:55], |v50|, s20
	v_cmp_lt_f32_e64 s[56:57], |v51|, s20
	v_cndmask_b32_e64 v48, v48, v192, s[4:5]
	v_cndmask_b32_e64 v49, v49, v193, s[50:51]
	v_cndmask_b32_e64 v50, v50, v194, s[54:55]
	v_cndmask_b32_e64 v51, v51, v195, s[56:57]
	v_cndmask_b32_e64 v192, 0, v177, vcc
	v_cndmask_b32_e64 v193, 0, v177, s[44:45]
	v_cndmask_b32_e64 v194, 0, v177, s[46:47]
	v_cndmask_b32_e64 v195, 0, v177, s[48:49]
	v_sub_f32_e32 v48, v48, v192
	v_sub_f32_e32 v49, v49, v193
	v_sub_f32_e32 v50, v50, v194
	v_sub_f32_e32 v51, v51, v195
	v_cmp_gt_f32_e64 vcc, s12, v40
	v_cmp_gt_f32_e64 s[44:45], s12, v41
	v_cmp_gt_f32_e64 s[46:47], s12, v42
	v_cmp_gt_f32_e64 s[48:49], s12, v43
	v_cndmask_b32_e64 v196, 0, 32, vcc
	v_cndmask_b32_e64 v197, 0, 32, s[44:45]
	v_cndmask_b32_e64 v198, 0, 32, s[46:47]
	v_cndmask_b32_e64 v199, 0, 32, s[48:49]
	v_ldexp_f32 v40, v40, v196
	v_ldexp_f32 v41, v41, v197
	v_ldexp_f32 v42, v42, v198
	v_ldexp_f32 v43, v43, v199
	v_log_f32_e32 v40, v40
	v_log_f32_e32 v41, v41
	v_log_f32_e32 v42, v42
	v_log_f32_e32 v43, v43
	v_mul_f32_e32 v196, s13, v40
	v_mul_f32_e32 v197, s13, v41
	v_mul_f32_e32 v198, s13, v42
	v_mul_f32_e32 v199, s13, v43
	v_fma_f32 v196, v40, s13, -v196
	v_fma_f32 v197, v41, s13, -v197
	v_fma_f32 v198, v42, s13, -v198
	v_fma_f32 v199, v43, s13, -v199
	v_fmac_f32_e32 v196, s99, v40
	v_fmac_f32_e32 v197, s99, v41
	v_fmac_f32_e32 v198, s99, v42
	v_fmac_f32_e32 v199, s99, v43
	v_fmac_f32_e32 v196, s13, v40
	v_fmac_f32_e32 v197, s13, v41
	v_fmac_f32_e32 v198, s13, v42
	v_fmac_f32_e32 v199, s13, v43
	v_cmp_lt_f32_e64 s[4:5], |v40|, s20
	v_cmp_lt_f32_e64 s[50:51], |v41|, s20
	v_cmp_lt_f32_e64 s[54:55], |v42|, s20
	v_cmp_lt_f32_e64 s[56:57], |v43|, s20
	v_cndmask_b32_e64 v40, v40, v196, s[4:5]
	v_cndmask_b32_e64 v41, v41, v197, s[50:51]
	v_cndmask_b32_e64 v42, v42, v198, s[54:55]
	v_cndmask_b32_e64 v43, v43, v199, s[56:57]
	v_cndmask_b32_e64 v196, 0, v177, vcc
	v_cndmask_b32_e64 v197, 0, v177, s[44:45]
	v_cndmask_b32_e64 v198, 0, v177, s[46:47]
	v_cndmask_b32_e64 v199, 0, v177, s[48:49]
	v_sub_f32_e32 v40, v40, v196
	v_sub_f32_e32 v41, v41, v197
	v_sub_f32_e32 v42, v42, v198
	v_sub_f32_e32 v43, v43, v199
	v_cvt_pk_bf16_f32 v48, v48, v49
	v_cvt_pk_bf16_f32 v49, v50, v51
	v_cvt_pk_bf16_f32 v50, v40, v41
	v_cvt_pk_bf16_f32 v51, v42, v43
	v_add_u32_e32 v155, 0x48000, v179
	global_store_dwordx4 v155, v[48:51], s[64:65]
	s_add_i32 s3, s3, -1
	s_cmp_eq_u32 s3, 0
	s_cbranch_scc1 .Lseg5_done
; __device__ __forceinline__ unsigned cvt_pk_bf16(float lo, float hi) { f32x2_t v = {lo, hi}; bf16x2_t b = __builtin_convertvector(v, bf16x2_t); return __builtin_bit_cast(unsigned, b); }
; __device__ __forceinline__ float sigmoidf_(float v) { return __builtin_amdgcn_rcpf(1.f + __expf(-v)); }
;     __device__ __forceinline__ void operator()(const f32x4 (&acc)[2][2][4][2], const pg8::Unit& u, int wr, int wc, int fr, int fq) const {
;     ...
;                     for (int m = 0; m < 4; ++m) {
;                         bf16_t* p = (bf16_t*)G + (size_t)(row0 + ai * 128 + m * 16) * 1024 + col;
;                         f32x4 a = acc[ai][bj][m][0], b = acc[ai][bj][m][1], ga, gb;
; #pragma unroll
;                         for (int j = 0; j < 4; ++j) { ga[j] = __logf(lb[j] + (1.f - lb[j]) * sigmoidf_(a[j])); gb[j] = __logf(lb[4 + j] + (1.f - lb[4 + j]) * sigmoidf_(b[j])); }
;                         u32x4 w; w.x = cvt_pk_bf16(ga[0], ga[1]); w.y = cvt_pk_bf16(ga[2], ga[3]); w.z = cvt_pk_bf16(gb[0], gb[1]); w.w = cvt_pk_bf16(gb[2], gb[3]);
;                         *(u32x4*)p = w;
.Lseg5_g6:
	v_mul_f32_e32 v36, s98, v36
	v_mul_f32_e32 v37, s98, v37
	v_mul_f32_e32 v38, s98, v38
	v_mul_f32_e32 v39, s98, v39
	v_mul_f32_e32 v28, s98, v28
	v_mul_f32_e32 v29, s98, v29
	v_mul_f32_e32 v30, s98, v30
	v_mul_f32_e32 v31, s98, v31
	v_exp_f32_e32 v36, v36
	v_exp_f32_e32 v37, v37
	v_exp_f32_e32 v38, v38
	v_exp_f32_e32 v39, v39
	v_exp_f32_e32 v28, v28
	v_exp_f32_e32 v29, v29
	v_exp_f32_e32 v30, v30
	v_exp_f32_e32 v31, v31
	v_add_f32_e32 v36, 1.0, v36
	v_add_f32_e32 v37, 1.0, v37
	v_add_f32_e32 v38, 1.0, v38
	v_add_f32_e32 v39, 1.0, v39
	v_add_f32_e32 v28, 1.0, v28
	v_add_f32_e32 v29, 1.0, v29
	v_add_f32_e32 v30, 1.0, v30
	v_add_f32_e32 v31, 1.0, v31
	v_rcp_f32_e32 v36, v36
	v_rcp_f32_e32 v37, v37
	v_rcp_f32_e32 v38, v38
	v_rcp_f32_e32 v39, v39
	v_rcp_f32_e32 v28, v28
	v_rcp_f32_e32 v29, v29
	v_rcp_f32_e32 v30, v30
	v_rcp_f32_e32 v31, v31
	v_fma_f32 v36, v36, v128, v156
	v_fma_f32 v37, v37, v129, v157
	v_fma_f32 v38, v38, v130, v158
	v_fma_f32 v39, v39, v131, v159
	v_fma_f32 v28, v28, v132, v160
	v_fma_f32 v29, v29, v133, v161
	v_fma_f32 v30, v30, v134, v162
	v_fma_f32 v31, v31, v135, v163
	v_cmp_gt_f32_e64 vcc, s12, v36
	v_cmp_gt_f32_e64 s[44:45], s12, v37
	v_cmp_gt_f32_e64 s[46:47], s12, v38
	v_cmp_gt_f32_e64 s[48:49], s12, v39
	v_cndmask_b32_e64 v192, 0, 32, vcc
	v_cndmask_b32_e64 v193, 0, 32, s[44:45]
	v_cndmask_b32_e64 v194, 0, 32, s[46:47]
	v_cndmask_b32_e64 v195, 0, 32, s[48:49]
	v_ldexp_f32 v36, v36, v192
	v_ldexp_f32 v37, v37, v193
	v_ldexp_f32 v38, v38, v194
	v_ldexp_f32 v39, v39, v195
	v_log_f32_e32 v36, v36
	v_log_f32_e32 v37, v37
	v_log_f32_e32 v38, v38
	v_log_f32_e32 v39, v39
	v_mul_f32_e32 v192, s13, v36
	v_mul_f32_e32 v193, s13, v37
	v_mul_f32_e32 v194, s13, v38
	v_mul_f32_e32 v195, s13, v39
	v_fma_f32 v192, v36, s13, -v192
	v_fma_f32 v193, v37, s13, -v193
	v_fma_f32 v194, v38, s13, -v194
	v_fma_f32 v195, v39, s13, -v195
	v_fmac_f32_e32 v192, s99, v36
	v_fmac_f32_e32 v193, s99, v37
	v_fmac_f32_e32 v194, s99, v38
	v_fmac_f32_e32 v195, s99, v39
	v_fmac_f32_e32 v192, s13, v36
	v_fmac_f32_e32 v193, s13, v37
	v_fmac_f32_e32 v194, s13, v38
	v_fmac_f32_e32 v195, s13, v39
	v_cmp_lt_f32_e64 s[4:5], |v36|, s20
	v_cmp_lt_f32_e64 s[50:51], |v37|, s20
	v_cmp_lt_f32_e64 s[54:55], |v38|, s20
	v_cmp_lt_f32_e64 s[56:57], |v39|, s20
	v_cndmask_b32_e64 v36, v36, v192, s[4:5]
	v_cndmask_b32_e64 v37, v37, v193, s[50:51]
	v_cndmask_b32_e64 v38, v38, v194, s[54:55]
	v_cndmask_b32_e64 v39, v39, v195, s[56:57]
	v_cndmask_b32_e64 v192, 0, v177, vcc
	v_cndmask_b32_e64 v193, 0, v177, s[44:45]
	v_cndmask_b32_e64 v194, 0, v177, s[46:47]
	v_cndmask_b32_e64 v195, 0, v177, s[48:49]
	v_sub_f32_e32 v36, v36, v192
	v_sub_f32_e32 v37, v37, v193
	v_sub_f32_e32 v38, v38, v194
	v_sub_f32_e32 v39, v39, v195
	v_cmp_gt_f32_e64 vcc, s12, v28
	v_cmp_gt_f32_e64 s[44:45], s12, v29
	v_cmp_gt_f32_e64 s[46:47], s12, v30
	v_cmp_gt_f32_e64 s[48:49], s12, v31
	v_cndmask_b32_e64 v196, 0, 32, vcc
	v_cndmask_b32_e64 v197, 0, 32, s[44:45]
	v_cndmask_b32_e64 v198, 0, 32, s[46:47]
	v_cndmask_b32_e64 v199, 0, 32, s[48:49]
	v_ldexp_f32 v28, v28, v196
	v_ldexp_f32 v29, v29, v197
	v_ldexp_f32 v30, v30, v198
	v_ldexp_f32 v31, v31, v199
	v_log_f32_e32 v28, v28
	v_log_f32_e32 v29, v29
	v_log_f32_e32 v30, v30
	v_log_f32_e32 v31, v31
	v_mul_f32_e32 v196, s13, v28
	v_mul_f32_e32 v197, s13, v29
	v_mul_f32_e32 v198, s13, v30
	v_mul_f32_e32 v199, s13, v31
	v_fma_f32 v196, v28, s13, -v196
	v_fma_f32 v197, v29, s13, -v197
	v_fma_f32 v198, v30, s13, -v198
	v_fma_f32 v199, v31, s13, -v199
	v_fmac_f32_e32 v196, s99, v28
	v_fmac_f32_e32 v197, s99, v29
	v_fmac_f32_e32 v198, s99, v30
	v_fmac_f32_e32 v199, s99, v31
	v_fmac_f32_e32 v196, s13, v28
	v_fmac_f32_e32 v197, s13, v29
	v_fmac_f32_e32 v198, s13, v30
	v_fmac_f32_e32 v199, s13, v31
	v_cmp_lt_f32_e64 s[4:5], |v28|, s20
	v_cmp_lt_f32_e64 s[50:51], |v29|, s20
	v_cmp_lt_f32_e64 s[54:55], |v30|, s20
	v_cmp_lt_f32_e64 s[56:57], |v31|, s20
	v_cndmask_b32_e64 v28, v28, v196, s[4:5]
	v_cndmask_b32_e64 v29, v29, v197, s[50:51]
	v_cndmask_b32_e64 v30, v30, v198, s[54:55]
	v_cndmask_b32_e64 v31, v31, v199, s[56:57]
	v_cndmask_b32_e64 v196, 0, v177, vcc
	v_cndmask_b32_e64 v197, 0, v177, s[44:45]
	v_cndmask_b32_e64 v198, 0, v177, s[46:47]
	v_cndmask_b32_e64 v199, 0, v177, s[48:49]
	v_sub_f32_e32 v28, v28, v196
	v_sub_f32_e32 v29, v29, v197
	v_sub_f32_e32 v30, v30, v198
	v_sub_f32_e32 v31, v31, v199
	v_cvt_pk_bf16_f32 v36, v36, v37
	v_cvt_pk_bf16_f32 v37, v38, v39
	v_cvt_pk_bf16_f32 v38, v28, v29
	v_cvt_pk_bf16_f32 v39, v30, v31
	v_add_u32_e32 v144, 0x50000, v179
	global_store_dwordx4 v144, v[36:39], s[64:65]
	s_add_i32 s3, s3, -1
	s_cmp_eq_u32 s3, 0
	s_cbranch_scc1 .Lseg5_done
; __device__ __forceinline__ unsigned cvt_pk_bf16(float lo, float hi) { f32x2_t v = {lo, hi}; bf16x2_t b = __builtin_convertvector(v, bf16x2_t); return __builtin_bit_cast(unsigned, b); }
; __device__ __forceinline__ float sigmoidf_(float v) { return __builtin_amdgcn_rcpf(1.f + __expf(-v)); }
;     __device__ __forceinline__ void operator()(const f32x4 (&acc)[2][2][4][2], const pg8::Unit& u, int wr, int wc, int fr, int fq) const {
;     ...
;                     for (int m = 0; m < 4; ++m) {
;                         bf16_t* p = (bf16_t*)G + (size_t)(row0 + ai * 128 + m * 16) * 1024 + col;
;                         f32x4 a = acc[ai][bj][m][0], b = acc[ai][bj][m][1], ga, gb;
; #pragma unroll
;                         for (int j = 0; j < 4; ++j) { ga[j] = __logf(lb[j] + (1.f - lb[j]) * sigmoidf_(a[j])); gb[j] = __logf(lb[4 + j] + (1.f - lb[4 + j]) * sigmoidf_(b[j])); }
;                         u32x4 w; w.x = cvt_pk_bf16(ga[0], ga[1]); w.y = cvt_pk_bf16(ga[2], ga[3]); w.z = cvt_pk_bf16(gb[0], gb[1]); w.w = cvt_pk_bf16(gb[2], gb[3]);
;                         *(u32x4*)p = w;
.Lseg5_g7:
	v_mul_f32_e32 v20, s98, v20
	v_mul_f32_e32 v21, s98, v21
	v_mul_f32_e32 v22, s98, v22
	v_mul_f32_e32 v23, s98, v23
	v_mul_f32_e32 v12, s98, v12
	v_mul_f32_e32 v13, s98, v13
	v_mul_f32_e32 v14, s98, v14
	v_mul_f32_e32 v15, s98, v15
	v_exp_f32_e32 v20, v20
	v_exp_f32_e32 v21, v21
	v_exp_f32_e32 v22, v22
	v_exp_f32_e32 v23, v23
	v_exp_f32_e32 v12, v12
	v_exp_f32_e32 v13, v13
	v_exp_f32_e32 v14, v14
	v_exp_f32_e32 v15, v15
	v_add_f32_e32 v20, 1.0, v20
	v_add_f32_e32 v21, 1.0, v21
	v_add_f32_e32 v22, 1.0, v22
	v_add_f32_e32 v23, 1.0, v23
	v_add_f32_e32 v12, 1.0, v12
	v_add_f32_e32 v13, 1.0, v13
	v_add_f32_e32 v14, 1.0, v14
	v_add_f32_e32 v15, 1.0, v15
	v_rcp_f32_e32 v20, v20
	v_rcp_f32_e32 v21, v21
	v_rcp_f32_e32 v22, v22
	v_rcp_f32_e32 v23, v23
	v_rcp_f32_e32 v12, v12
	v_rcp_f32_e32 v13, v13
	v_rcp_f32_e32 v14, v14
	v_rcp_f32_e32 v15, v15
	v_fma_f32 v20, v20, v128, v156
	v_fma_f32 v21, v21, v129, v157
	v_fma_f32 v22, v22, v130, v158
	v_fma_f32 v23, v23, v131, v159
	v_fma_f32 v12, v12, v132, v160
	v_fma_f32 v13, v13, v133, v161
	v_fma_f32 v14, v14, v134, v162
	v_fma_f32 v15, v15, v135, v163
	v_cmp_gt_f32_e64 vcc, s12, v20
	v_cmp_gt_f32_e64 s[44:45], s12, v21
	v_cmp_gt_f32_e64 s[46:47], s12, v22
	v_cmp_gt_f32_e64 s[48:49], s12, v23
	v_cndmask_b32_e64 v192, 0, 32, vcc
	v_cndmask_b32_e64 v193, 0, 32, s[44:45]
	v_cndmask_b32_e64 v194, 0, 32, s[46:47]
	v_cndmask_b32_e64 v195, 0, 32, s[48:49]
	v_ldexp_f32 v20, v20, v192
	v_ldexp_f32 v21, v21, v193
	v_ldexp_f32 v22, v22, v194
	v_ldexp_f32 v23, v23, v195
	v_log_f32_e32 v20, v20
	v_log_f32_e32 v21, v21
	v_log_f32_e32 v22, v22
	v_log_f32_e32 v23, v23
	v_mul_f32_e32 v192, s13, v20
	v_mul_f32_e32 v193, s13, v21
	v_mul_f32_e32 v194, s13, v22
	v_mul_f32_e32 v195, s13, v23
	v_fma_f32 v192, v20, s13, -v192
	v_fma_f32 v193, v21, s13, -v193
	v_fma_f32 v194, v22, s13, -v194
	v_fma_f32 v195, v23, s13, -v195
	v_fmac_f32_e32 v192, s99, v20
	v_fmac_f32_e32 v193, s99, v21
	v_fmac_f32_e32 v194, s99, v22
	v_fmac_f32_e32 v195, s99, v23
	v_fmac_f32_e32 v192, s13, v20
	v_fmac_f32_e32 v193, s13, v21
	v_fmac_f32_e32 v194, s13, v22
	v_fmac_f32_e32 v195, s13, v23
	v_cmp_lt_f32_e64 s[4:5], |v20|, s20
	v_cmp_lt_f32_e64 s[50:51], |v21|, s20
	v_cmp_lt_f32_e64 s[54:55], |v22|, s20
	v_cmp_lt_f32_e64 s[56:57], |v23|, s20
	v_cndmask_b32_e64 v20, v20, v192, s[4:5]
	v_cndmask_b32_e64 v21, v21, v193, s[50:51]
	v_cndmask_b32_e64 v22, v22, v194, s[54:55]
	v_cndmask_b32_e64 v23, v23, v195, s[56:57]
	v_cndmask_b32_e64 v192, 0, v177, vcc
	v_cndmask_b32_e64 v193, 0, v177, s[44:45]
	v_cndmask_b32_e64 v194, 0, v177, s[46:47]
	v_cndmask_b32_e64 v195, 0, v177, s[48:49]
	v_sub_f32_e32 v20, v20, v192
	v_sub_f32_e32 v21, v21, v193
	v_sub_f32_e32 v22, v22, v194
	v_sub_f32_e32 v23, v23, v195
	v_cmp_gt_f32_e64 vcc, s12, v12
	v_cmp_gt_f32_e64 s[44:45], s12, v13
	v_cmp_gt_f32_e64 s[46:47], s12, v14
	v_cmp_gt_f32_e64 s[48:49], s12, v15
	v_cndmask_b32_e64 v196, 0, 32, vcc
	v_cndmask_b32_e64 v197, 0, 32, s[44:45]
	v_cndmask_b32_e64 v198, 0, 32, s[46:47]
	v_cndmask_b32_e64 v199, 0, 32, s[48:49]
	v_ldexp_f32 v12, v12, v196
	v_ldexp_f32 v13, v13, v197
	v_ldexp_f32 v14, v14, v198
	v_ldexp_f32 v15, v15, v199
	v_log_f32_e32 v12, v12
	v_log_f32_e32 v13, v13
	v_log_f32_e32 v14, v14
	v_log_f32_e32 v15, v15
	v_mul_f32_e32 v196, s13, v12
	v_mul_f32_e32 v197, s13, v13
	v_mul_f32_e32 v198, s13, v14
	v_mul_f32_e32 v199, s13, v15
	v_fma_f32 v196, v12, s13, -v196
	v_fma_f32 v197, v13, s13, -v197
	v_fma_f32 v198, v14, s13, -v198
	v_fma_f32 v199, v15, s13, -v199
	v_fmac_f32_e32 v196, s99, v12
	v_fmac_f32_e32 v197, s99, v13
	v_fmac_f32_e32 v198, s99, v14
	v_fmac_f32_e32 v199, s99, v15
	v_fmac_f32_e32 v196, s13, v12
	v_fmac_f32_e32 v197, s13, v13
	v_fmac_f32_e32 v198, s13, v14
	v_fmac_f32_e32 v199, s13, v15
	v_cmp_lt_f32_e64 s[4:5], |v12|, s20
	v_cmp_lt_f32_e64 s[50:51], |v13|, s20
	v_cmp_lt_f32_e64 s[54:55], |v14|, s20
	v_cmp_lt_f32_e64 s[56:57], |v15|, s20
	v_cndmask_b32_e64 v12, v12, v196, s[4:5]
	v_cndmask_b32_e64 v13, v13, v197, s[50:51]
	v_cndmask_b32_e64 v14, v14, v198, s[54:55]
	v_cndmask_b32_e64 v15, v15, v199, s[56:57]
	v_cndmask_b32_e64 v196, 0, v177, vcc
	v_cndmask_b32_e64 v197, 0, v177, s[44:45]
	v_cndmask_b32_e64 v198, 0, v177, s[46:47]
	v_cndmask_b32_e64 v199, 0, v177, s[48:49]
	v_sub_f32_e32 v12, v12, v196
	v_sub_f32_e32 v13, v13, v197
	v_sub_f32_e32 v14, v14, v198
	v_sub_f32_e32 v15, v15, v199
	v_cvt_pk_bf16_f32 v20, v20, v21
	v_cvt_pk_bf16_f32 v21, v22, v23
	v_cvt_pk_bf16_f32 v22, v12, v13
	v_cvt_pk_bf16_f32 v23, v14, v15
	v_add_u32_e32 v155, 0x58000, v179
	global_store_dwordx4 v155, v[20:23], s[64:65]
	s_add_i32 s3, s3, -1
	s_cmp_eq_u32 s3, 0
	s_cbranch_scc1 .Lseg5_done
; __device__ __forceinline__ unsigned cvt_pk_bf16(float lo, float hi) { f32x2_t v = {lo, hi}; bf16x2_t b = __builtin_convertvector(v, bf16x2_t); return __builtin_bit_cast(unsigned, b); }
; __device__ __forceinline__ float sigmoidf_(float v) { return __builtin_amdgcn_rcpf(1.f + __expf(-v)); }
;     __device__ __forceinline__ void operator()(const f32x4 (&acc)[2][2][4][2], const pg8::Unit& u, int wr, int wc, int fr, int fq) const {
;     ...
;                     for (int m = 0; m < 4; ++m) {
;                         bf16_t* p = (bf16_t*)G + (size_t)(row0 + ai * 128 + m * 16) * 1024 + col;
;                         f32x4 a = acc[ai][bj][m][0], b = acc[ai][bj][m][1], ga, gb;
; #pragma unroll
;                         for (int j = 0; j < 4; ++j) { ga[j] = __logf(lb[j] + (1.f - lb[j]) * sigmoidf_(a[j])); gb[j] = __logf(lb[4 + j] + (1.f - lb[4 + j]) * sigmoidf_(b[j])); }
;                         u32x4 w; w.x = cvt_pk_bf16(ga[0], ga[1]); w.y = cvt_pk_bf16(ga[2], ga[3]); w.z = cvt_pk_bf16(gb[0], gb[1]); w.w = cvt_pk_bf16(gb[2], gb[3]);
;                         *(u32x4*)p = w;
.Lseg5_g8:
	v_mul_f32_e32 v116, s98, v116
	v_mul_f32_e32 v117, s98, v117
	v_mul_f32_e32 v118, s98, v118
	v_mul_f32_e32 v119, s98, v119
	v_mul_f32_e32 v108, s98, v108
	v_mul_f32_e32 v109, s98, v109
	v_mul_f32_e32 v110, s98, v110
	v_mul_f32_e32 v111, s98, v111
	v_exp_f32_e32 v116, v116
	v_exp_f32_e32 v117, v117
	v_exp_f32_e32 v118, v118
	v_exp_f32_e32 v119, v119
	v_exp_f32_e32 v108, v108
	v_exp_f32_e32 v109, v109
	v_exp_f32_e32 v110, v110
	v_exp_f32_e32 v111, v111
	v_add_f32_e32 v116, 1.0, v116
	v_add_f32_e32 v117, 1.0, v117
	v_add_f32_e32 v118, 1.0, v118
	v_add_f32_e32 v119, 1.0, v119
	v_add_f32_e32 v108, 1.0, v108
	v_add_f32_e32 v109, 1.0, v109
	v_add_f32_e32 v110, 1.0, v110
	v_add_f32_e32 v111, 1.0, v111
	v_rcp_f32_e32 v116, v116
	v_rcp_f32_e32 v117, v117
	v_rcp_f32_e32 v118, v118
	v_rcp_f32_e32 v119, v119
	v_rcp_f32_e32 v108, v108
	v_rcp_f32_e32 v109, v109
	v_rcp_f32_e32 v110, v110
	v_rcp_f32_e32 v111, v111
	v_fma_f32 v116, v116, v164, v184
	v_fma_f32 v117, v117, v165, v185
	v_fma_f32 v118, v118, v166, v186
	v_fma_f32 v119, v119, v167, v187
	v_fma_f32 v108, v108, v180, v188
	v_fma_f32 v109, v109, v181, v189
	v_fma_f32 v110, v110, v182, v190
	v_fma_f32 v111, v111, v183, v191
	v_cmp_gt_f32_e64 vcc, s12, v116
	v_cmp_gt_f32_e64 s[44:45], s12, v117
	v_cmp_gt_f32_e64 s[46:47], s12, v118
	v_cmp_gt_f32_e64 s[48:49], s12, v119
	v_cndmask_b32_e64 v192, 0, 32, vcc
	v_cndmask_b32_e64 v193, 0, 32, s[44:45]
	v_cndmask_b32_e64 v194, 0, 32, s[46:47]
	v_cndmask_b32_e64 v195, 0, 32, s[48:49]
	v_ldexp_f32 v116, v116, v192
	v_ldexp_f32 v117, v117, v193
	v_ldexp_f32 v118, v118, v194
	v_ldexp_f32 v119, v119, v195
	v_log_f32_e32 v116, v116
	v_log_f32_e32 v117, v117
	v_log_f32_e32 v118, v118
	v_log_f32_e32 v119, v119
	v_mul_f32_e32 v192, s13, v116
	v_mul_f32_e32 v193, s13, v117
	v_mul_f32_e32 v194, s13, v118
	v_mul_f32_e32 v195, s13, v119
	v_fma_f32 v192, v116, s13, -v192
	v_fma_f32 v193, v117, s13, -v193
	v_fma_f32 v194, v118, s13, -v194
	v_fma_f32 v195, v119, s13, -v195
	v_fmac_f32_e32 v192, s99, v116
	v_fmac_f32_e32 v193, s99, v117
	v_fmac_f32_e32 v194, s99, v118
	v_fmac_f32_e32 v195, s99, v119
	v_fmac_f32_e32 v192, s13, v116
	v_fmac_f32_e32 v193, s13, v117
	v_fmac_f32_e32 v194, s13, v118
	v_fmac_f32_e32 v195, s13, v119
	v_cmp_lt_f32_e64 s[4:5], |v116|, s20
	v_cmp_lt_f32_e64 s[50:51], |v117|, s20
	v_cmp_lt_f32_e64 s[54:55], |v118|, s20
	v_cmp_lt_f32_e64 s[56:57], |v119|, s20
	v_cndmask_b32_e64 v116, v116, v192, s[4:5]
	v_cndmask_b32_e64 v117, v117, v193, s[50:51]
	v_cndmask_b32_e64 v118, v118, v194, s[54:55]
	v_cndmask_b32_e64 v119, v119, v195, s[56:57]
	v_cndmask_b32_e64 v192, 0, v177, vcc
	v_cndmask_b32_e64 v193, 0, v177, s[44:45]
	v_cndmask_b32_e64 v194, 0, v177, s[46:47]
	v_cndmask_b32_e64 v195, 0, v177, s[48:49]
	v_sub_f32_e32 v116, v116, v192
	v_sub_f32_e32 v117, v117, v193
	v_sub_f32_e32 v118, v118, v194
	v_sub_f32_e32 v119, v119, v195
	v_cmp_gt_f32_e64 vcc, s12, v108
	v_cmp_gt_f32_e64 s[44:45], s12, v109
	v_cmp_gt_f32_e64 s[46:47], s12, v110
	v_cmp_gt_f32_e64 s[48:49], s12, v111
	v_cndmask_b32_e64 v196, 0, 32, vcc
	v_cndmask_b32_e64 v197, 0, 32, s[44:45]
	v_cndmask_b32_e64 v198, 0, 32, s[46:47]
	v_cndmask_b32_e64 v199, 0, 32, s[48:49]
	v_ldexp_f32 v108, v108, v196
	v_ldexp_f32 v109, v109, v197
	v_ldexp_f32 v110, v110, v198
	v_ldexp_f32 v111, v111, v199
	v_log_f32_e32 v108, v108
	v_log_f32_e32 v109, v109
	v_log_f32_e32 v110, v110
	v_log_f32_e32 v111, v111
	v_mul_f32_e32 v196, s13, v108
	v_mul_f32_e32 v197, s13, v109
	v_mul_f32_e32 v198, s13, v110
	v_mul_f32_e32 v199, s13, v111
	v_fma_f32 v196, v108, s13, -v196
	v_fma_f32 v197, v109, s13, -v197
	v_fma_f32 v198, v110, s13, -v198
	v_fma_f32 v199, v111, s13, -v199
	v_fmac_f32_e32 v196, s99, v108
	v_fmac_f32_e32 v197, s99, v109
	v_fmac_f32_e32 v198, s99, v110
	v_fmac_f32_e32 v199, s99, v111
	v_fmac_f32_e32 v196, s13, v108
	v_fmac_f32_e32 v197, s13, v109
	v_fmac_f32_e32 v198, s13, v110
	v_fmac_f32_e32 v199, s13, v111
	v_cmp_lt_f32_e64 s[4:5], |v108|, s20
	v_cmp_lt_f32_e64 s[50:51], |v109|, s20
	v_cmp_lt_f32_e64 s[54:55], |v110|, s20
	v_cmp_lt_f32_e64 s[56:57], |v111|, s20
	v_cndmask_b32_e64 v108, v108, v196, s[4:5]
	v_cndmask_b32_e64 v109, v109, v197, s[50:51]
	v_cndmask_b32_e64 v110, v110, v198, s[54:55]
	v_cndmask_b32_e64 v111, v111, v199, s[56:57]
	v_cndmask_b32_e64 v196, 0, v177, vcc
	v_cndmask_b32_e64 v197, 0, v177, s[44:45]
	v_cndmask_b32_e64 v198, 0, v177, s[46:47]
	v_cndmask_b32_e64 v199, 0, v177, s[48:49]
	v_sub_f32_e32 v108, v108, v196
	v_sub_f32_e32 v109, v109, v197
	v_sub_f32_e32 v110, v110, v198
	v_sub_f32_e32 v111, v111, v199
	v_cvt_pk_bf16_f32 v116, v116, v117
	v_cvt_pk_bf16_f32 v117, v118, v119
	v_cvt_pk_bf16_f32 v118, v108, v109
	v_cvt_pk_bf16_f32 v119, v110, v111
	v_mov_b32_e32 v144, v179
	global_store_dwordx4 v144, v[116:119], s[64:65] offset:256
	s_add_i32 s3, s3, -1
	s_cmp_eq_u32 s3, 0
	s_cbranch_scc1 .Lseg5_done
; __device__ __forceinline__ unsigned cvt_pk_bf16(float lo, float hi) { f32x2_t v = {lo, hi}; bf16x2_t b = __builtin_convertvector(v, bf16x2_t); return __builtin_bit_cast(unsigned, b); }
; __device__ __forceinline__ float sigmoidf_(float v) { return __builtin_amdgcn_rcpf(1.f + __expf(-v)); }
;     __device__ __forceinline__ void operator()(const f32x4 (&acc)[2][2][4][2], const pg8::Unit& u, int wr, int wc, int fr, int fq) const {
;     ...
;                     for (int m = 0; m < 4; ++m) {
;                         bf16_t* p = (bf16_t*)G + (size_t)(row0 + ai * 128 + m * 16) * 1024 + col;
;                         f32x4 a = acc[ai][bj][m][0], b = acc[ai][bj][m][1], ga, gb;
; #pragma unroll
;                         for (int j = 0; j < 4; ++j) { ga[j] = __logf(lb[j] + (1.f - lb[j]) * sigmoidf_(a[j])); gb[j] = __logf(lb[4 + j] + (1.f - lb[4 + j]) * sigmoidf_(b[j])); }
;                         u32x4 w; w.x = cvt_pk_bf16(ga[0], ga[1]); w.y = cvt_pk_bf16(ga[2], ga[3]); w.z = cvt_pk_bf16(gb[0], gb[1]); w.w = cvt_pk_bf16(gb[2], gb[3]);
;                         *(u32x4*)p = w;
.Lseg5_g9:
	v_mul_f32_e32 v96, s98, v96
	v_mul_f32_e32 v97, s98, v97
	v_mul_f32_e32 v98, s98, v98
	v_mul_f32_e32 v99, s98, v99
	v_mul_f32_e32 v88, s98, v88
	v_mul_f32_e32 v89, s98, v89
	v_mul_f32_e32 v90, s98, v90
	v_mul_f32_e32 v91, s98, v91
	v_exp_f32_e32 v96, v96
	v_exp_f32_e32 v97, v97
	v_exp_f32_e32 v98, v98
	v_exp_f32_e32 v99, v99
	v_exp_f32_e32 v88, v88
	v_exp_f32_e32 v89, v89
	v_exp_f32_e32 v90, v90
	v_exp_f32_e32 v91, v91
	v_add_f32_e32 v96, 1.0, v96
	v_add_f32_e32 v97, 1.0, v97
	v_add_f32_e32 v98, 1.0, v98
	v_add_f32_e32 v99, 1.0, v99
	v_add_f32_e32 v88, 1.0, v88
	v_add_f32_e32 v89, 1.0, v89
	v_add_f32_e32 v90, 1.0, v90
	v_add_f32_e32 v91, 1.0, v91
	v_rcp_f32_e32 v96, v96
	v_rcp_f32_e32 v97, v97
	v_rcp_f32_e32 v98, v98
	v_rcp_f32_e32 v99, v99
	v_rcp_f32_e32 v88, v88
	v_rcp_f32_e32 v89, v89
	v_rcp_f32_e32 v90, v90
	v_rcp_f32_e32 v91, v91
	v_fma_f32 v96, v96, v164, v184
	v_fma_f32 v97, v97, v165, v185
	v_fma_f32 v98, v98, v166, v186
	v_fma_f32 v99, v99, v167, v187
	v_fma_f32 v88, v88, v180, v188
	v_fma_f32 v89, v89, v181, v189
	v_fma_f32 v90, v90, v182, v190
	v_fma_f32 v91, v91, v183, v191
	v_cmp_gt_f32_e64 vcc, s12, v96
	v_cmp_gt_f32_e64 s[44:45], s12, v97
	v_cmp_gt_f32_e64 s[46:47], s12, v98
	v_cmp_gt_f32_e64 s[48:49], s12, v99
	v_cndmask_b32_e64 v192, 0, 32, vcc
	v_cndmask_b32_e64 v193, 0, 32, s[44:45]
	v_cndmask_b32_e64 v194, 0, 32, s[46:47]
	v_cndmask_b32_e64 v195, 0, 32, s[48:49]
	v_ldexp_f32 v96, v96, v192
	v_ldexp_f32 v97, v97, v193
	v_ldexp_f32 v98, v98, v194
	v_ldexp_f32 v99, v99, v195
	v_log_f32_e32 v96, v96
	v_log_f32_e32 v97, v97
	v_log_f32_e32 v98, v98
	v_log_f32_e32 v99, v99
	v_mul_f32_e32 v192, s13, v96
	v_mul_f32_e32 v193, s13, v97
	v_mul_f32_e32 v194, s13, v98
	v_mul_f32_e32 v195, s13, v99
	v_fma_f32 v192, v96, s13, -v192
	v_fma_f32 v193, v97, s13, -v193
	v_fma_f32 v194, v98, s13, -v194
	v_fma_f32 v195, v99, s13, -v195
	v_fmac_f32_e32 v192, s99, v96
	v_fmac_f32_e32 v193, s99, v97
	v_fmac_f32_e32 v194, s99, v98
	v_fmac_f32_e32 v195, s99, v99
	v_fmac_f32_e32 v192, s13, v96
	v_fmac_f32_e32 v193, s13, v97
	v_fmac_f32_e32 v194, s13, v98
	v_fmac_f32_e32 v195, s13, v99
	v_cmp_lt_f32_e64 s[4:5], |v96|, s20
	v_cmp_lt_f32_e64 s[50:51], |v97|, s20
	v_cmp_lt_f32_e64 s[54:55], |v98|, s20
	v_cmp_lt_f32_e64 s[56:57], |v99|, s20
	v_cndmask_b32_e64 v96, v96, v192, s[4:5]
	v_cndmask_b32_e64 v97, v97, v193, s[50:51]
	v_cndmask_b32_e64 v98, v98, v194, s[54:55]
	v_cndmask_b32_e64 v99, v99, v195, s[56:57]
	v_cndmask_b32_e64 v192, 0, v177, vcc
	v_cndmask_b32_e64 v193, 0, v177, s[44:45]
	v_cndmask_b32_e64 v194, 0, v177, s[46:47]
	v_cndmask_b32_e64 v195, 0, v177, s[48:49]
	v_sub_f32_e32 v96, v96, v192
	v_sub_f32_e32 v97, v97, v193
	v_sub_f32_e32 v98, v98, v194
	v_sub_f32_e32 v99, v99, v195
	v_cmp_gt_f32_e64 vcc, s12, v88
	v_cmp_gt_f32_e64 s[44:45], s12, v89
	v_cmp_gt_f32_e64 s[46:47], s12, v90
	v_cmp_gt_f32_e64 s[48:49], s12, v91
	v_cndmask_b32_e64 v196, 0, 32, vcc
	v_cndmask_b32_e64 v197, 0, 32, s[44:45]
	v_cndmask_b32_e64 v198, 0, 32, s[46:47]
	v_cndmask_b32_e64 v199, 0, 32, s[48:49]
	v_ldexp_f32 v88, v88, v196
	v_ldexp_f32 v89, v89, v197
	v_ldexp_f32 v90, v90, v198
	v_ldexp_f32 v91, v91, v199
	v_log_f32_e32 v88, v88
	v_log_f32_e32 v89, v89
	v_log_f32_e32 v90, v90
	v_log_f32_e32 v91, v91
	v_mul_f32_e32 v196, s13, v88
	v_mul_f32_e32 v197, s13, v89
	v_mul_f32_e32 v198, s13, v90
	v_mul_f32_e32 v199, s13, v91
	v_fma_f32 v196, v88, s13, -v196
	v_fma_f32 v197, v89, s13, -v197
	v_fma_f32 v198, v90, s13, -v198
	v_fma_f32 v199, v91, s13, -v199
	v_fmac_f32_e32 v196, s99, v88
	v_fmac_f32_e32 v197, s99, v89
	v_fmac_f32_e32 v198, s99, v90
	v_fmac_f32_e32 v199, s99, v91
	v_fmac_f32_e32 v196, s13, v88
	v_fmac_f32_e32 v197, s13, v89
	v_fmac_f32_e32 v198, s13, v90
	v_fmac_f32_e32 v199, s13, v91
	v_cmp_lt_f32_e64 s[4:5], |v88|, s20
	v_cmp_lt_f32_e64 s[50:51], |v89|, s20
	v_cmp_lt_f32_e64 s[54:55], |v90|, s20
	v_cmp_lt_f32_e64 s[56:57], |v91|, s20
	v_cndmask_b32_e64 v88, v88, v196, s[4:5]
	v_cndmask_b32_e64 v89, v89, v197, s[50:51]
	v_cndmask_b32_e64 v90, v90, v198, s[54:55]
	v_cndmask_b32_e64 v91, v91, v199, s[56:57]
	v_cndmask_b32_e64 v196, 0, v177, vcc
	v_cndmask_b32_e64 v197, 0, v177, s[44:45]
	v_cndmask_b32_e64 v198, 0, v177, s[46:47]
	v_cndmask_b32_e64 v199, 0, v177, s[48:49]
	v_sub_f32_e32 v88, v88, v196
	v_sub_f32_e32 v89, v89, v197
	v_sub_f32_e32 v90, v90, v198
	v_sub_f32_e32 v91, v91, v199
	v_cvt_pk_bf16_f32 v96, v96, v97
	v_cvt_pk_bf16_f32 v97, v98, v99
	v_cvt_pk_bf16_f32 v98, v88, v89
	v_cvt_pk_bf16_f32 v99, v90, v91
	v_add_u32_e32 v155, 0x8000, v179
	global_store_dwordx4 v155, v[96:99], s[64:65] offset:256
	s_add_i32 s3, s3, -1
	s_cmp_eq_u32 s3, 0
	s_cbranch_scc1 .Lseg5_done
; __device__ __forceinline__ unsigned cvt_pk_bf16(float lo, float hi) { f32x2_t v = {lo, hi}; bf16x2_t b = __builtin_convertvector(v, bf16x2_t); return __builtin_bit_cast(unsigned, b); }
; __device__ __forceinline__ float sigmoidf_(float v) { return __builtin_amdgcn_rcpf(1.f + __expf(-v)); }
;     __device__ __forceinline__ void operator()(const f32x4 (&acc)[2][2][4][2], const pg8::Unit& u, int wr, int wc, int fr, int fq) const {
;     ...
;                     for (int m = 0; m < 4; ++m) {
;                         bf16_t* p = (bf16_t*)G + (size_t)(row0 + ai * 128 + m * 16) * 1024 + col;
;                         f32x4 a = acc[ai][bj][m][0], b = acc[ai][bj][m][1], ga, gb;
; #pragma unroll
;                         for (int j = 0; j < 4; ++j) { ga[j] = __logf(lb[j] + (1.f - lb[j]) * sigmoidf_(a[j])); gb[j] = __logf(lb[4 + j] + (1.f - lb[4 + j]) * sigmoidf_(b[j])); }
;                         u32x4 w; w.x = cvt_pk_bf16(ga[0], ga[1]); w.y = cvt_pk_bf16(ga[2], ga[3]); w.z = cvt_pk_bf16(gb[0], gb[1]); w.w = cvt_pk_bf16(gb[2], gb[3]);
;                         *(u32x4*)p = w;
.Lseg5_g10:
	v_mul_f32_e32 v80, s98, v80
	v_mul_f32_e32 v81, s98, v81
	v_mul_f32_e32 v82, s98, v82
	v_mul_f32_e32 v83, s98, v83
	v_mul_f32_e32 v72, s98, v72
	v_mul_f32_e32 v73, s98, v73
	v_mul_f32_e32 v74, s98, v74
	v_mul_f32_e32 v75, s98, v75
	v_exp_f32_e32 v80, v80
	v_exp_f32_e32 v81, v81
	v_exp_f32_e32 v82, v82
	v_exp_f32_e32 v83, v83
	v_exp_f32_e32 v72, v72
	v_exp_f32_e32 v73, v73
	v_exp_f32_e32 v74, v74
	v_exp_f32_e32 v75, v75
	v_add_f32_e32 v80, 1.0, v80
	v_add_f32_e32 v81, 1.0, v81
	v_add_f32_e32 v82, 1.0, v82
	v_add_f32_e32 v83, 1.0, v83
	v_add_f32_e32 v72, 1.0, v72
	v_add_f32_e32 v73, 1.0, v73
	v_add_f32_e32 v74, 1.0, v74
	v_add_f32_e32 v75, 1.0, v75
	v_rcp_f32_e32 v80, v80
	v_rcp_f32_e32 v81, v81
	v_rcp_f32_e32 v82, v82
	v_rcp_f32_e32 v83, v83
	v_rcp_f32_e32 v72, v72
	v_rcp_f32_e32 v73, v73
	v_rcp_f32_e32 v74, v74
	v_rcp_f32_e32 v75, v75
	v_fma_f32 v80, v80, v164, v184
	v_fma_f32 v81, v81, v165, v185
	v_fma_f32 v82, v82, v166, v186
	v_fma_f32 v83, v83, v167, v187
	v_fma_f32 v72, v72, v180, v188
	v_fma_f32 v73, v73, v181, v189
	v_fma_f32 v74, v74, v182, v190
	v_fma_f32 v75, v75, v183, v191
	v_cmp_gt_f32_e64 vcc, s12, v80
	v_cmp_gt_f32_e64 s[44:45], s12, v81
	v_cmp_gt_f32_e64 s[46:47], s12, v82
	v_cmp_gt_f32_e64 s[48:49], s12, v83
	v_cndmask_b32_e64 v192, 0, 32, vcc
	v_cndmask_b32_e64 v193, 0, 32, s[44:45]
	v_cndmask_b32_e64 v194, 0, 32, s[46:47]
	v_cndmask_b32_e64 v195, 0, 32, s[48:49]
	v_ldexp_f32 v80, v80, v192
	v_ldexp_f32 v81, v81, v193
	v_ldexp_f32 v82, v82, v194
	v_ldexp_f32 v83, v83, v195
	v_log_f32_e32 v80, v80
	v_log_f32_e32 v81, v81
	v_log_f32_e32 v82, v82
	v_log_f32_e32 v83, v83
	v_mul_f32_e32 v192, s13, v80
	v_mul_f32_e32 v193, s13, v81
	v_mul_f32_e32 v194, s13, v82
	v_mul_f32_e32 v195, s13, v83
	v_fma_f32 v192, v80, s13, -v192
	v_fma_f32 v193, v81, s13, -v193
	v_fma_f32 v194, v82, s13, -v194
	v_fma_f32 v195, v83, s13, -v195
	v_fmac_f32_e32 v192, s99, v80
	v_fmac_f32_e32 v193, s99, v81
	v_fmac_f32_e32 v194, s99, v82
	v_fmac_f32_e32 v195, s99, v83
	v_fmac_f32_e32 v192, s13, v80
	v_fmac_f32_e32 v193, s13, v81
	v_fmac_f32_e32 v194, s13, v82
	v_fmac_f32_e32 v195, s13, v83
	v_cmp_lt_f32_e64 s[4:5], |v80|, s20
	v_cmp_lt_f32_e64 s[50:51], |v81|, s20
	v_cmp_lt_f32_e64 s[54:55], |v82|, s20
	v_cmp_lt_f32_e64 s[56:57], |v83|, s20
	v_cndmask_b32_e64 v80, v80, v192, s[4:5]
	v_cndmask_b32_e64 v81, v81, v193, s[50:51]
	v_cndmask_b32_e64 v82, v82, v194, s[54:55]
	v_cndmask_b32_e64 v83, v83, v195, s[56:57]
	v_cndmask_b32_e64 v192, 0, v177, vcc
	v_cndmask_b32_e64 v193, 0, v177, s[44:45]
	v_cndmask_b32_e64 v194, 0, v177, s[46:47]
	v_cndmask_b32_e64 v195, 0, v177, s[48:49]
	v_sub_f32_e32 v80, v80, v192
	v_sub_f32_e32 v81, v81, v193
	v_sub_f32_e32 v82, v82, v194
	v_sub_f32_e32 v83, v83, v195
	v_cmp_gt_f32_e64 vcc, s12, v72
	v_cmp_gt_f32_e64 s[44:45], s12, v73
	v_cmp_gt_f32_e64 s[46:47], s12, v74
	v_cmp_gt_f32_e64 s[48:49], s12, v75
	v_cndmask_b32_e64 v196, 0, 32, vcc
	v_cndmask_b32_e64 v197, 0, 32, s[44:45]
	v_cndmask_b32_e64 v198, 0, 32, s[46:47]
	v_cndmask_b32_e64 v199, 0, 32, s[48:49]
	v_ldexp_f32 v72, v72, v196
	v_ldexp_f32 v73, v73, v197
	v_ldexp_f32 v74, v74, v198
	v_ldexp_f32 v75, v75, v199
	v_log_f32_e32 v72, v72
	v_log_f32_e32 v73, v73
	v_log_f32_e32 v74, v74
	v_log_f32_e32 v75, v75
	v_mul_f32_e32 v196, s13, v72
	v_mul_f32_e32 v197, s13, v73
	v_mul_f32_e32 v198, s13, v74
	v_mul_f32_e32 v199, s13, v75
	v_fma_f32 v196, v72, s13, -v196
	v_fma_f32 v197, v73, s13, -v197
	v_fma_f32 v198, v74, s13, -v198
	v_fma_f32 v199, v75, s13, -v199
	v_fmac_f32_e32 v196, s99, v72
	v_fmac_f32_e32 v197, s99, v73
	v_fmac_f32_e32 v198, s99, v74
	v_fmac_f32_e32 v199, s99, v75
	v_fmac_f32_e32 v196, s13, v72
	v_fmac_f32_e32 v197, s13, v73
	v_fmac_f32_e32 v198, s13, v74
	v_fmac_f32_e32 v199, s13, v75
	v_cmp_lt_f32_e64 s[4:5], |v72|, s20
	v_cmp_lt_f32_e64 s[50:51], |v73|, s20
	v_cmp_lt_f32_e64 s[54:55], |v74|, s20
	v_cmp_lt_f32_e64 s[56:57], |v75|, s20
	v_cndmask_b32_e64 v72, v72, v196, s[4:5]
	v_cndmask_b32_e64 v73, v73, v197, s[50:51]
	v_cndmask_b32_e64 v74, v74, v198, s[54:55]
	v_cndmask_b32_e64 v75, v75, v199, s[56:57]
	v_cndmask_b32_e64 v196, 0, v177, vcc
	v_cndmask_b32_e64 v197, 0, v177, s[44:45]
	v_cndmask_b32_e64 v198, 0, v177, s[46:47]
	v_cndmask_b32_e64 v199, 0, v177, s[48:49]
	v_sub_f32_e32 v72, v72, v196
	v_sub_f32_e32 v73, v73, v197
	v_sub_f32_e32 v74, v74, v198
	v_sub_f32_e32 v75, v75, v199
	v_cvt_pk_bf16_f32 v80, v80, v81
	v_cvt_pk_bf16_f32 v81, v82, v83
	v_cvt_pk_bf16_f32 v82, v72, v73
	v_cvt_pk_bf16_f32 v83, v74, v75
	v_add_u32_e32 v144, 0x10000, v179
	global_store_dwordx4 v144, v[80:83], s[64:65] offset:256
	s_add_i32 s3, s3, -1
	s_cmp_eq_u32 s3, 0
	s_cbranch_scc1 .Lseg5_done
; __device__ __forceinline__ unsigned cvt_pk_bf16(float lo, float hi) { f32x2_t v = {lo, hi}; bf16x2_t b = __builtin_convertvector(v, bf16x2_t); return __builtin_bit_cast(unsigned, b); }
; __device__ __forceinline__ float sigmoidf_(float v) { return __builtin_amdgcn_rcpf(1.f + __expf(-v)); }
;     __device__ __forceinline__ void operator()(const f32x4 (&acc)[2][2][4][2], const pg8::Unit& u, int wr, int wc, int fr, int fq) const {
;     ...
;                     for (int m = 0; m < 4; ++m) {
;                         bf16_t* p = (bf16_t*)G + (size_t)(row0 + ai * 128 + m * 16) * 1024 + col;
;                         f32x4 a = acc[ai][bj][m][0], b = acc[ai][bj][m][1], ga, gb;
; #pragma unroll
;                         for (int j = 0; j < 4; ++j) { ga[j] = __logf(lb[j] + (1.f - lb[j]) * sigmoidf_(a[j])); gb[j] = __logf(lb[4 + j] + (1.f - lb[4 + j]) * sigmoidf_(b[j])); }
;                         u32x4 w; w.x = cvt_pk_bf16(ga[0], ga[1]); w.y = cvt_pk_bf16(ga[2], ga[3]); w.z = cvt_pk_bf16(gb[0], gb[1]); w.w = cvt_pk_bf16(gb[2], gb[3]);
;                         *(u32x4*)p = w;
.Lseg5_g11:
	v_mul_f32_e32 v68, s98, v68
	v_mul_f32_e32 v69, s98, v69
	v_mul_f32_e32 v70, s98, v70
	v_mul_f32_e32 v71, s98, v71
	v_mul_f32_e32 v64, s98, v64
	v_mul_f32_e32 v65, s98, v65
	v_mul_f32_e32 v66, s98, v66
	v_mul_f32_e32 v67, s98, v67
	v_exp_f32_e32 v68, v68
	v_exp_f32_e32 v69, v69
	v_exp_f32_e32 v70, v70
	v_exp_f32_e32 v71, v71
	v_exp_f32_e32 v64, v64
	v_exp_f32_e32 v65, v65
	v_exp_f32_e32 v66, v66
	v_exp_f32_e32 v67, v67
	v_add_f32_e32 v68, 1.0, v68
	v_add_f32_e32 v69, 1.0, v69
	v_add_f32_e32 v70, 1.0, v70
	v_add_f32_e32 v71, 1.0, v71
	v_add_f32_e32 v64, 1.0, v64
	v_add_f32_e32 v65, 1.0, v65
	v_add_f32_e32 v66, 1.0, v66
	v_add_f32_e32 v67, 1.0, v67
	v_rcp_f32_e32 v68, v68
	v_rcp_f32_e32 v69, v69
	v_rcp_f32_e32 v70, v70
	v_rcp_f32_e32 v71, v71
	v_rcp_f32_e32 v64, v64
	v_rcp_f32_e32 v65, v65
	v_rcp_f32_e32 v66, v66
	v_rcp_f32_e32 v67, v67
	v_fma_f32 v68, v68, v164, v184
	v_fma_f32 v69, v69, v165, v185
	v_fma_f32 v70, v70, v166, v186
	v_fma_f32 v71, v71, v167, v187
	v_fma_f32 v64, v64, v180, v188
	v_fma_f32 v65, v65, v181, v189
	v_fma_f32 v66, v66, v182, v190
	v_fma_f32 v67, v67, v183, v191
	v_cmp_gt_f32_e64 vcc, s12, v68
	v_cmp_gt_f32_e64 s[44:45], s12, v69
	v_cmp_gt_f32_e64 s[46:47], s12, v70
	v_cmp_gt_f32_e64 s[48:49], s12, v71
	v_cndmask_b32_e64 v192, 0, 32, vcc
	v_cndmask_b32_e64 v193, 0, 32, s[44:45]
	v_cndmask_b32_e64 v194, 0, 32, s[46:47]
	v_cndmask_b32_e64 v195, 0, 32, s[48:49]
	v_ldexp_f32 v68, v68, v192
	v_ldexp_f32 v69, v69, v193
	v_ldexp_f32 v70, v70, v194
	v_ldexp_f32 v71, v71, v195
	v_log_f32_e32 v68, v68
	v_log_f32_e32 v69, v69
	v_log_f32_e32 v70, v70
	v_log_f32_e32 v71, v71
	v_mul_f32_e32 v192, s13, v68
	v_mul_f32_e32 v193, s13, v69
	v_mul_f32_e32 v194, s13, v70
	v_mul_f32_e32 v195, s13, v71
	v_fma_f32 v192, v68, s13, -v192
	v_fma_f32 v193, v69, s13, -v193
	v_fma_f32 v194, v70, s13, -v194
	v_fma_f32 v195, v71, s13, -v195
	v_fmac_f32_e32 v192, s99, v68
	v_fmac_f32_e32 v193, s99, v69
	v_fmac_f32_e32 v194, s99, v70
	v_fmac_f32_e32 v195, s99, v71
	v_fmac_f32_e32 v192, s13, v68
	v_fmac_f32_e32 v193, s13, v69
	v_fmac_f32_e32 v194, s13, v70
	v_fmac_f32_e32 v195, s13, v71
	v_cmp_lt_f32_e64 s[4:5], |v68|, s20
	v_cmp_lt_f32_e64 s[50:51], |v69|, s20
	v_cmp_lt_f32_e64 s[54:55], |v70|, s20
	v_cmp_lt_f32_e64 s[56:57], |v71|, s20
	v_cndmask_b32_e64 v68, v68, v192, s[4:5]
	v_cndmask_b32_e64 v69, v69, v193, s[50:51]
	v_cndmask_b32_e64 v70, v70, v194, s[54:55]
	v_cndmask_b32_e64 v71, v71, v195, s[56:57]
	v_cndmask_b32_e64 v192, 0, v177, vcc
	v_cndmask_b32_e64 v193, 0, v177, s[44:45]
	v_cndmask_b32_e64 v194, 0, v177, s[46:47]
	v_cndmask_b32_e64 v195, 0, v177, s[48:49]
	v_sub_f32_e32 v68, v68, v192
	v_sub_f32_e32 v69, v69, v193
	v_sub_f32_e32 v70, v70, v194
	v_sub_f32_e32 v71, v71, v195
	v_cmp_gt_f32_e64 vcc, s12, v64
	v_cmp_gt_f32_e64 s[44:45], s12, v65
	v_cmp_gt_f32_e64 s[46:47], s12, v66
	v_cmp_gt_f32_e64 s[48:49], s12, v67
	v_cndmask_b32_e64 v196, 0, 32, vcc
	v_cndmask_b32_e64 v197, 0, 32, s[44:45]
	v_cndmask_b32_e64 v198, 0, 32, s[46:47]
	v_cndmask_b32_e64 v199, 0, 32, s[48:49]
	v_ldexp_f32 v64, v64, v196
	v_ldexp_f32 v65, v65, v197
	v_ldexp_f32 v66, v66, v198
	v_ldexp_f32 v67, v67, v199
	v_log_f32_e32 v64, v64
	v_log_f32_e32 v65, v65
	v_log_f32_e32 v66, v66
	v_log_f32_e32 v67, v67
	v_mul_f32_e32 v196, s13, v64
	v_mul_f32_e32 v197, s13, v65
	v_mul_f32_e32 v198, s13, v66
	v_mul_f32_e32 v199, s13, v67
	v_fma_f32 v196, v64, s13, -v196
	v_fma_f32 v197, v65, s13, -v197
	v_fma_f32 v198, v66, s13, -v198
	v_fma_f32 v199, v67, s13, -v199
	v_fmac_f32_e32 v196, s99, v64
	v_fmac_f32_e32 v197, s99, v65
	v_fmac_f32_e32 v198, s99, v66
	v_fmac_f32_e32 v199, s99, v67
	v_fmac_f32_e32 v196, s13, v64
	v_fmac_f32_e32 v197, s13, v65
	v_fmac_f32_e32 v198, s13, v66
	v_fmac_f32_e32 v199, s13, v67
	v_cmp_lt_f32_e64 s[4:5], |v64|, s20
	v_cmp_lt_f32_e64 s[50:51], |v65|, s20
	v_cmp_lt_f32_e64 s[54:55], |v66|, s20
	v_cmp_lt_f32_e64 s[56:57], |v67|, s20
	v_cndmask_b32_e64 v64, v64, v196, s[4:5]
	v_cndmask_b32_e64 v65, v65, v197, s[50:51]
	v_cndmask_b32_e64 v66, v66, v198, s[54:55]
	v_cndmask_b32_e64 v67, v67, v199, s[56:57]
	v_cndmask_b32_e64 v196, 0, v177, vcc
	v_cndmask_b32_e64 v197, 0, v177, s[44:45]
	v_cndmask_b32_e64 v198, 0, v177, s[46:47]
	v_cndmask_b32_e64 v199, 0, v177, s[48:49]
	v_sub_f32_e32 v64, v64, v196
	v_sub_f32_e32 v65, v65, v197
	v_sub_f32_e32 v66, v66, v198
	v_sub_f32_e32 v67, v67, v199
	v_cvt_pk_bf16_f32 v68, v68, v69
	v_cvt_pk_bf16_f32 v69, v70, v71
	v_cvt_pk_bf16_f32 v70, v64, v65
	v_cvt_pk_bf16_f32 v71, v66, v67
	v_add_u32_e32 v155, 0x18000, v179
	global_store_dwordx4 v155, v[68:71], s[64:65] offset:256
	s_add_i32 s3, s3, -1
	s_cmp_eq_u32 s3, 0
	s_cbranch_scc1 .Lseg5_done
; __device__ __forceinline__ unsigned cvt_pk_bf16(float lo, float hi) { f32x2_t v = {lo, hi}; bf16x2_t b = __builtin_convertvector(v, bf16x2_t); return __builtin_bit_cast(unsigned, b); }
; __device__ __forceinline__ float sigmoidf_(float v) { return __builtin_amdgcn_rcpf(1.f + __expf(-v)); }
;     __device__ __forceinline__ void operator()(const f32x4 (&acc)[2][2][4][2], const pg8::Unit& u, int wr, int wc, int fr, int fq) const {
;     ...
;                     for (int m = 0; m < 4; ++m) {
;                         bf16_t* p = (bf16_t*)G + (size_t)(row0 + ai * 128 + m * 16) * 1024 + col;
;                         f32x4 a = acc[ai][bj][m][0], b = acc[ai][bj][m][1], ga, gb;
; #pragma unroll
;                         for (int j = 0; j < 4; ++j) { ga[j] = __logf(lb[j] + (1.f - lb[j]) * sigmoidf_(a[j])); gb[j] = __logf(lb[4 + j] + (1.f - lb[4 + j]) * sigmoidf_(b[j])); }
;                         u32x4 w; w.x = cvt_pk_bf16(ga[0], ga[1]); w.y = cvt_pk_bf16(ga[2], ga[3]); w.z = cvt_pk_bf16(gb[0], gb[1]); w.w = cvt_pk_bf16(gb[2], gb[3]);
;                         *(u32x4*)p = w;
.Lseg5_g12:
	v_mul_f32_e32 v52, s98, v52
	v_mul_f32_e32 v53, s98, v53
	v_mul_f32_e32 v54, s98, v54
	v_mul_f32_e32 v55, s98, v55
	v_mul_f32_e32 v44, s98, v44
	v_mul_f32_e32 v45, s98, v45
	v_mul_f32_e32 v46, s98, v46
	v_mul_f32_e32 v47, s98, v47
	v_exp_f32_e32 v52, v52
	v_exp_f32_e32 v53, v53
	v_exp_f32_e32 v54, v54
	v_exp_f32_e32 v55, v55
	v_exp_f32_e32 v44, v44
	v_exp_f32_e32 v45, v45
	v_exp_f32_e32 v46, v46
	v_exp_f32_e32 v47, v47
	v_add_f32_e32 v52, 1.0, v52
	v_add_f32_e32 v53, 1.0, v53
	v_add_f32_e32 v54, 1.0, v54
	v_add_f32_e32 v55, 1.0, v55
	v_add_f32_e32 v44, 1.0, v44
	v_add_f32_e32 v45, 1.0, v45
	v_add_f32_e32 v46, 1.0, v46
	v_add_f32_e32 v47, 1.0, v47
	v_rcp_f32_e32 v52, v52
	v_rcp_f32_e32 v53, v53
	v_rcp_f32_e32 v54, v54
	v_rcp_f32_e32 v55, v55
	v_rcp_f32_e32 v44, v44
	v_rcp_f32_e32 v45, v45
	v_rcp_f32_e32 v46, v46
	v_rcp_f32_e32 v47, v47
	v_fma_f32 v52, v52, v164, v184
	v_fma_f32 v53, v53, v165, v185
	v_fma_f32 v54, v54, v166, v186
	v_fma_f32 v55, v55, v167, v187
	v_fma_f32 v44, v44, v180, v188
	v_fma_f32 v45, v45, v181, v189
	v_fma_f32 v46, v46, v182, v190
	v_fma_f32 v47, v47, v183, v191
	v_cmp_gt_f32_e64 vcc, s12, v52
	v_cmp_gt_f32_e64 s[44:45], s12, v53
	v_cmp_gt_f32_e64 s[46:47], s12, v54
	v_cmp_gt_f32_e64 s[48:49], s12, v55
	v_cndmask_b32_e64 v192, 0, 32, vcc
	v_cndmask_b32_e64 v193, 0, 32, s[44:45]
	v_cndmask_b32_e64 v194, 0, 32, s[46:47]
	v_cndmask_b32_e64 v195, 0, 32, s[48:49]
	v_ldexp_f32 v52, v52, v192
	v_ldexp_f32 v53, v53, v193
	v_ldexp_f32 v54, v54, v194
	v_ldexp_f32 v55, v55, v195
	v_log_f32_e32 v52, v52
	v_log_f32_e32 v53, v53
	v_log_f32_e32 v54, v54
	v_log_f32_e32 v55, v55
	v_mul_f32_e32 v192, s13, v52
	v_mul_f32_e32 v193, s13, v53
	v_mul_f32_e32 v194, s13, v54
	v_mul_f32_e32 v195, s13, v55
	v_fma_f32 v192, v52, s13, -v192
	v_fma_f32 v193, v53, s13, -v193
	v_fma_f32 v194, v54, s13, -v194
	v_fma_f32 v195, v55, s13, -v195
	v_fmac_f32_e32 v192, s99, v52
	v_fmac_f32_e32 v193, s99, v53
	v_fmac_f32_e32 v194, s99, v54
	v_fmac_f32_e32 v195, s99, v55
	v_fmac_f32_e32 v192, s13, v52
	v_fmac_f32_e32 v193, s13, v53
	v_fmac_f32_e32 v194, s13, v54
	v_fmac_f32_e32 v195, s13, v55
	v_cmp_lt_f32_e64 s[4:5], |v52|, s20
	v_cmp_lt_f32_e64 s[50:51], |v53|, s20
	v_cmp_lt_f32_e64 s[54:55], |v54|, s20
	v_cmp_lt_f32_e64 s[56:57], |v55|, s20
	v_cndmask_b32_e64 v52, v52, v192, s[4:5]
	v_cndmask_b32_e64 v53, v53, v193, s[50:51]
	v_cndmask_b32_e64 v54, v54, v194, s[54:55]
	v_cndmask_b32_e64 v55, v55, v195, s[56:57]
	v_cndmask_b32_e64 v192, 0, v177, vcc
	v_cndmask_b32_e64 v193, 0, v177, s[44:45]
	v_cndmask_b32_e64 v194, 0, v177, s[46:47]
	v_cndmask_b32_e64 v195, 0, v177, s[48:49]
	v_sub_f32_e32 v52, v52, v192
	v_sub_f32_e32 v53, v53, v193
	v_sub_f32_e32 v54, v54, v194
	v_sub_f32_e32 v55, v55, v195
	v_cmp_gt_f32_e64 vcc, s12, v44
	v_cmp_gt_f32_e64 s[44:45], s12, v45
	v_cmp_gt_f32_e64 s[46:47], s12, v46
	v_cmp_gt_f32_e64 s[48:49], s12, v47
	v_cndmask_b32_e64 v196, 0, 32, vcc
	v_cndmask_b32_e64 v197, 0, 32, s[44:45]
	v_cndmask_b32_e64 v198, 0, 32, s[46:47]
	v_cndmask_b32_e64 v199, 0, 32, s[48:49]
	v_ldexp_f32 v44, v44, v196
	v_ldexp_f32 v45, v45, v197
	v_ldexp_f32 v46, v46, v198
	v_ldexp_f32 v47, v47, v199
	v_log_f32_e32 v44, v44
	v_log_f32_e32 v45, v45
	v_log_f32_e32 v46, v46
	v_log_f32_e32 v47, v47
	v_mul_f32_e32 v196, s13, v44
	v_mul_f32_e32 v197, s13, v45
	v_mul_f32_e32 v198, s13, v46
	v_mul_f32_e32 v199, s13, v47
	v_fma_f32 v196, v44, s13, -v196
	v_fma_f32 v197, v45, s13, -v197
	v_fma_f32 v198, v46, s13, -v198
	v_fma_f32 v199, v47, s13, -v199
	v_fmac_f32_e32 v196, s99, v44
	v_fmac_f32_e32 v197, s99, v45
	v_fmac_f32_e32 v198, s99, v46
	v_fmac_f32_e32 v199, s99, v47
	v_fmac_f32_e32 v196, s13, v44
	v_fmac_f32_e32 v197, s13, v45
	v_fmac_f32_e32 v198, s13, v46
	v_fmac_f32_e32 v199, s13, v47
	v_cmp_lt_f32_e64 s[4:5], |v44|, s20
	v_cmp_lt_f32_e64 s[50:51], |v45|, s20
	v_cmp_lt_f32_e64 s[54:55], |v46|, s20
	v_cmp_lt_f32_e64 s[56:57], |v47|, s20
	v_cndmask_b32_e64 v44, v44, v196, s[4:5]
	v_cndmask_b32_e64 v45, v45, v197, s[50:51]
	v_cndmask_b32_e64 v46, v46, v198, s[54:55]
	v_cndmask_b32_e64 v47, v47, v199, s[56:57]
	v_cndmask_b32_e64 v196, 0, v177, vcc
	v_cndmask_b32_e64 v197, 0, v177, s[44:45]
	v_cndmask_b32_e64 v198, 0, v177, s[46:47]
	v_cndmask_b32_e64 v199, 0, v177, s[48:49]
	v_sub_f32_e32 v44, v44, v196
	v_sub_f32_e32 v45, v45, v197
	v_sub_f32_e32 v46, v46, v198
	v_sub_f32_e32 v47, v47, v199
	v_cvt_pk_bf16_f32 v52, v52, v53
	v_cvt_pk_bf16_f32 v53, v54, v55
	v_cvt_pk_bf16_f32 v54, v44, v45
	v_cvt_pk_bf16_f32 v55, v46, v47
	v_add_u32_e32 v144, 0x40000, v179
	global_store_dwordx4 v144, v[52:55], s[64:65] offset:256
	s_add_i32 s3, s3, -1
	s_cmp_eq_u32 s3, 0
	s_cbranch_scc1 .Lseg5_done
; __device__ __forceinline__ unsigned cvt_pk_bf16(float lo, float hi) { f32x2_t v = {lo, hi}; bf16x2_t b = __builtin_convertvector(v, bf16x2_t); return __builtin_bit_cast(unsigned, b); }
; __device__ __forceinline__ float sigmoidf_(float v) { return __builtin_amdgcn_rcpf(1.f + __expf(-v)); }
;     __device__ __forceinline__ void operator()(const f32x4 (&acc)[2][2][4][2], const pg8::Unit& u, int wr, int wc, int fr, int fq) const {
;     ...
;                     for (int m = 0; m < 4; ++m) {
;                         bf16_t* p = (bf16_t*)G + (size_t)(row0 + ai * 128 + m * 16) * 1024 + col;
;                         f32x4 a = acc[ai][bj][m][0], b = acc[ai][bj][m][1], ga, gb;
; #pragma unroll
;                         for (int j = 0; j < 4; ++j) { ga[j] = __logf(lb[j] + (1.f - lb[j]) * sigmoidf_(a[j])); gb[j] = __logf(lb[4 + j] + (1.f - lb[4 + j]) * sigmoidf_(b[j])); }
;                         u32x4 w; w.x = cvt_pk_bf16(ga[0], ga[1]); w.y = cvt_pk_bf16(ga[2], ga[3]); w.z = cvt_pk_bf16(gb[0], gb[1]); w.w = cvt_pk_bf16(gb[2], gb[3]);
;                         *(u32x4*)p = w;
.Lseg5_g13:
	v_mul_f32_e32 v32, s98, v32
	v_mul_f32_e32 v33, s98, v33
	v_mul_f32_e32 v34, s98, v34
	v_mul_f32_e32 v35, s98, v35
	v_mul_f32_e32 v24, s98, v24
	v_mul_f32_e32 v25, s98, v25
	v_mul_f32_e32 v26, s98, v26
	v_mul_f32_e32 v27, s98, v27
	v_exp_f32_e32 v32, v32
	v_exp_f32_e32 v33, v33
	v_exp_f32_e32 v34, v34
	v_exp_f32_e32 v35, v35
	v_exp_f32_e32 v24, v24
	v_exp_f32_e32 v25, v25
	v_exp_f32_e32 v26, v26
	v_exp_f32_e32 v27, v27
	v_add_f32_e32 v32, 1.0, v32
	v_add_f32_e32 v33, 1.0, v33
	v_add_f32_e32 v34, 1.0, v34
	v_add_f32_e32 v35, 1.0, v35
	v_add_f32_e32 v24, 1.0, v24
	v_add_f32_e32 v25, 1.0, v25
	v_add_f32_e32 v26, 1.0, v26
	v_add_f32_e32 v27, 1.0, v27
	v_rcp_f32_e32 v32, v32
	v_rcp_f32_e32 v33, v33
	v_rcp_f32_e32 v34, v34
	v_rcp_f32_e32 v35, v35
	v_rcp_f32_e32 v24, v24
	v_rcp_f32_e32 v25, v25
	v_rcp_f32_e32 v26, v26
	v_rcp_f32_e32 v27, v27
	v_fma_f32 v32, v32, v164, v184
	v_fma_f32 v33, v33, v165, v185
	v_fma_f32 v34, v34, v166, v186
	v_fma_f32 v35, v35, v167, v187
	v_fma_f32 v24, v24, v180, v188
	v_fma_f32 v25, v25, v181, v189
	v_fma_f32 v26, v26, v182, v190
	v_fma_f32 v27, v27, v183, v191
	v_cmp_gt_f32_e64 vcc, s12, v32
	v_cmp_gt_f32_e64 s[44:45], s12, v33
	v_cmp_gt_f32_e64 s[46:47], s12, v34
	v_cmp_gt_f32_e64 s[48:49], s12, v35
	v_cndmask_b32_e64 v192, 0, 32, vcc
	v_cndmask_b32_e64 v193, 0, 32, s[44:45]
	v_cndmask_b32_e64 v194, 0, 32, s[46:47]
	v_cndmask_b32_e64 v195, 0, 32, s[48:49]
	v_ldexp_f32 v32, v32, v192
	v_ldexp_f32 v33, v33, v193
	v_ldexp_f32 v34, v34, v194
	v_ldexp_f32 v35, v35, v195
	v_log_f32_e32 v32, v32
	v_log_f32_e32 v33, v33
	v_log_f32_e32 v34, v34
	v_log_f32_e32 v35, v35
	v_mul_f32_e32 v192, s13, v32
	v_mul_f32_e32 v193, s13, v33
	v_mul_f32_e32 v194, s13, v34
	v_mul_f32_e32 v195, s13, v35
	v_fma_f32 v192, v32, s13, -v192
	v_fma_f32 v193, v33, s13, -v193
	v_fma_f32 v194, v34, s13, -v194
	v_fma_f32 v195, v35, s13, -v195
	v_fmac_f32_e32 v192, s99, v32
	v_fmac_f32_e32 v193, s99, v33
	v_fmac_f32_e32 v194, s99, v34
	v_fmac_f32_e32 v195, s99, v35
	v_fmac_f32_e32 v192, s13, v32
	v_fmac_f32_e32 v193, s13, v33
	v_fmac_f32_e32 v194, s13, v34
	v_fmac_f32_e32 v195, s13, v35
	v_cmp_lt_f32_e64 s[4:5], |v32|, s20
	v_cmp_lt_f32_e64 s[50:51], |v33|, s20
	v_cmp_lt_f32_e64 s[54:55], |v34|, s20
	v_cmp_lt_f32_e64 s[56:57], |v35|, s20
	v_cndmask_b32_e64 v32, v32, v192, s[4:5]
	v_cndmask_b32_e64 v33, v33, v193, s[50:51]
	v_cndmask_b32_e64 v34, v34, v194, s[54:55]
	v_cndmask_b32_e64 v35, v35, v195, s[56:57]
	v_cndmask_b32_e64 v192, 0, v177, vcc
	v_cndmask_b32_e64 v193, 0, v177, s[44:45]
	v_cndmask_b32_e64 v194, 0, v177, s[46:47]
	v_cndmask_b32_e64 v195, 0, v177, s[48:49]
	v_sub_f32_e32 v32, v32, v192
	v_sub_f32_e32 v33, v33, v193
	v_sub_f32_e32 v34, v34, v194
	v_sub_f32_e32 v35, v35, v195
	v_cmp_gt_f32_e64 vcc, s12, v24
	v_cmp_gt_f32_e64 s[44:45], s12, v25
	v_cmp_gt_f32_e64 s[46:47], s12, v26
	v_cmp_gt_f32_e64 s[48:49], s12, v27
	v_cndmask_b32_e64 v196, 0, 32, vcc
	v_cndmask_b32_e64 v197, 0, 32, s[44:45]
	v_cndmask_b32_e64 v198, 0, 32, s[46:47]
	v_cndmask_b32_e64 v199, 0, 32, s[48:49]
	v_ldexp_f32 v24, v24, v196
	v_ldexp_f32 v25, v25, v197
	v_ldexp_f32 v26, v26, v198
	v_ldexp_f32 v27, v27, v199
	v_log_f32_e32 v24, v24
	v_log_f32_e32 v25, v25
	v_log_f32_e32 v26, v26
	v_log_f32_e32 v27, v27
	v_mul_f32_e32 v196, s13, v24
	v_mul_f32_e32 v197, s13, v25
	v_mul_f32_e32 v198, s13, v26
	v_mul_f32_e32 v199, s13, v27
	v_fma_f32 v196, v24, s13, -v196
	v_fma_f32 v197, v25, s13, -v197
	v_fma_f32 v198, v26, s13, -v198
	v_fma_f32 v199, v27, s13, -v199
	v_fmac_f32_e32 v196, s99, v24
	v_fmac_f32_e32 v197, s99, v25
	v_fmac_f32_e32 v198, s99, v26
	v_fmac_f32_e32 v199, s99, v27
	v_fmac_f32_e32 v196, s13, v24
	v_fmac_f32_e32 v197, s13, v25
	v_fmac_f32_e32 v198, s13, v26
	v_fmac_f32_e32 v199, s13, v27
	v_cmp_lt_f32_e64 s[4:5], |v24|, s20
	v_cmp_lt_f32_e64 s[50:51], |v25|, s20
	v_cmp_lt_f32_e64 s[54:55], |v26|, s20
	v_cmp_lt_f32_e64 s[56:57], |v27|, s20
	v_cndmask_b32_e64 v24, v24, v196, s[4:5]
	v_cndmask_b32_e64 v25, v25, v197, s[50:51]
	v_cndmask_b32_e64 v26, v26, v198, s[54:55]
	v_cndmask_b32_e64 v27, v27, v199, s[56:57]
	v_cndmask_b32_e64 v196, 0, v177, vcc
	v_cndmask_b32_e64 v197, 0, v177, s[44:45]
	v_cndmask_b32_e64 v198, 0, v177, s[46:47]
	v_cndmask_b32_e64 v199, 0, v177, s[48:49]
	v_sub_f32_e32 v24, v24, v196
	v_sub_f32_e32 v25, v25, v197
	v_sub_f32_e32 v26, v26, v198
	v_sub_f32_e32 v27, v27, v199
	v_cvt_pk_bf16_f32 v32, v32, v33
	v_cvt_pk_bf16_f32 v33, v34, v35
	v_cvt_pk_bf16_f32 v34, v24, v25
	v_cvt_pk_bf16_f32 v35, v26, v27
	v_add_u32_e32 v155, 0x48000, v179
	global_store_dwordx4 v155, v[32:35], s[64:65] offset:256
	s_add_i32 s3, s3, -1
	s_cmp_eq_u32 s3, 0
	s_cbranch_scc1 .Lseg5_done
; __device__ __forceinline__ unsigned cvt_pk_bf16(float lo, float hi) { f32x2_t v = {lo, hi}; bf16x2_t b = __builtin_convertvector(v, bf16x2_t); return __builtin_bit_cast(unsigned, b); }
; __device__ __forceinline__ float sigmoidf_(float v) { return __builtin_amdgcn_rcpf(1.f + __expf(-v)); }
;     __device__ __forceinline__ void operator()(const f32x4 (&acc)[2][2][4][2], const pg8::Unit& u, int wr, int wc, int fr, int fq) const {
;     ...
;                     for (int m = 0; m < 4; ++m) {
;                         bf16_t* p = (bf16_t*)G + (size_t)(row0 + ai * 128 + m * 16) * 1024 + col;
;                         f32x4 a = acc[ai][bj][m][0], b = acc[ai][bj][m][1], ga, gb;
; #pragma unroll
;                         for (int j = 0; j < 4; ++j) { ga[j] = __logf(lb[j] + (1.f - lb[j]) * sigmoidf_(a[j])); gb[j] = __logf(lb[4 + j] + (1.f - lb[4 + j]) * sigmoidf_(b[j])); }
;                         u32x4 w; w.x = cvt_pk_bf16(ga[0], ga[1]); w.y = cvt_pk_bf16(ga[2], ga[3]); w.z = cvt_pk_bf16(gb[0], gb[1]); w.w = cvt_pk_bf16(gb[2], gb[3]);
;                         *(u32x4*)p = w;
.Lseg5_g14:
	v_mul_f32_e32 v16, s98, v16
	v_mul_f32_e32 v17, s98, v17
	v_mul_f32_e32 v18, s98, v18
	v_mul_f32_e32 v19, s98, v19
	v_mul_f32_e32 v8, s98, v8
	v_mul_f32_e32 v9, s98, v9
	v_mul_f32_e32 v10, s98, v10
	v_mul_f32_e32 v11, s98, v11
	v_exp_f32_e32 v16, v16
	v_exp_f32_e32 v17, v17
	v_exp_f32_e32 v18, v18
	v_exp_f32_e32 v19, v19
	v_exp_f32_e32 v8, v8
	v_exp_f32_e32 v9, v9
	v_exp_f32_e32 v10, v10
	v_exp_f32_e32 v11, v11
	v_add_f32_e32 v16, 1.0, v16
	v_add_f32_e32 v17, 1.0, v17
	v_add_f32_e32 v18, 1.0, v18
	v_add_f32_e32 v19, 1.0, v19
	v_add_f32_e32 v8, 1.0, v8
	v_add_f32_e32 v9, 1.0, v9
	v_add_f32_e32 v10, 1.0, v10
	v_add_f32_e32 v11, 1.0, v11
	v_rcp_f32_e32 v16, v16
	v_rcp_f32_e32 v17, v17
	v_rcp_f32_e32 v18, v18
	v_rcp_f32_e32 v19, v19
	v_rcp_f32_e32 v8, v8
	v_rcp_f32_e32 v9, v9
	v_rcp_f32_e32 v10, v10
	v_rcp_f32_e32 v11, v11
	v_fma_f32 v16, v16, v164, v184
	v_fma_f32 v17, v17, v165, v185
	v_fma_f32 v18, v18, v166, v186
	v_fma_f32 v19, v19, v167, v187
	v_fma_f32 v8, v8, v180, v188
	v_fma_f32 v9, v9, v181, v189
	v_fma_f32 v10, v10, v182, v190
	v_fma_f32 v11, v11, v183, v191
	v_cmp_gt_f32_e64 vcc, s12, v16
	v_cmp_gt_f32_e64 s[44:45], s12, v17
	v_cmp_gt_f32_e64 s[46:47], s12, v18
	v_cmp_gt_f32_e64 s[48:49], s12, v19
	v_cndmask_b32_e64 v192, 0, 32, vcc
	v_cndmask_b32_e64 v193, 0, 32, s[44:45]
	v_cndmask_b32_e64 v194, 0, 32, s[46:47]
	v_cndmask_b32_e64 v195, 0, 32, s[48:49]
	v_ldexp_f32 v16, v16, v192
	v_ldexp_f32 v17, v17, v193
	v_ldexp_f32 v18, v18, v194
	v_ldexp_f32 v19, v19, v195
	v_log_f32_e32 v16, v16
	v_log_f32_e32 v17, v17
	v_log_f32_e32 v18, v18
	v_log_f32_e32 v19, v19
	v_mul_f32_e32 v192, s13, v16
	v_mul_f32_e32 v193, s13, v17
	v_mul_f32_e32 v194, s13, v18
	v_mul_f32_e32 v195, s13, v19
	v_fma_f32 v192, v16, s13, -v192
	v_fma_f32 v193, v17, s13, -v193
	v_fma_f32 v194, v18, s13, -v194
	v_fma_f32 v195, v19, s13, -v195
	v_fmac_f32_e32 v192, s99, v16
	v_fmac_f32_e32 v193, s99, v17
	v_fmac_f32_e32 v194, s99, v18
	v_fmac_f32_e32 v195, s99, v19
	v_fmac_f32_e32 v192, s13, v16
	v_fmac_f32_e32 v193, s13, v17
	v_fmac_f32_e32 v194, s13, v18
	v_fmac_f32_e32 v195, s13, v19
	v_cmp_lt_f32_e64 s[4:5], |v16|, s20
	v_cmp_lt_f32_e64 s[50:51], |v17|, s20
	v_cmp_lt_f32_e64 s[54:55], |v18|, s20
	v_cmp_lt_f32_e64 s[56:57], |v19|, s20
	v_cndmask_b32_e64 v16, v16, v192, s[4:5]
	v_cndmask_b32_e64 v17, v17, v193, s[50:51]
	v_cndmask_b32_e64 v18, v18, v194, s[54:55]
	v_cndmask_b32_e64 v19, v19, v195, s[56:57]
	v_cndmask_b32_e64 v192, 0, v177, vcc
	v_cndmask_b32_e64 v193, 0, v177, s[44:45]
	v_cndmask_b32_e64 v194, 0, v177, s[46:47]
	v_cndmask_b32_e64 v195, 0, v177, s[48:49]
	v_sub_f32_e32 v16, v16, v192
	v_sub_f32_e32 v17, v17, v193
	v_sub_f32_e32 v18, v18, v194
	v_sub_f32_e32 v19, v19, v195
	v_cmp_gt_f32_e64 vcc, s12, v8
	v_cmp_gt_f32_e64 s[44:45], s12, v9
	v_cmp_gt_f32_e64 s[46:47], s12, v10
	v_cmp_gt_f32_e64 s[48:49], s12, v11
	v_cndmask_b32_e64 v196, 0, 32, vcc
	v_cndmask_b32_e64 v197, 0, 32, s[44:45]
	v_cndmask_b32_e64 v198, 0, 32, s[46:47]
	v_cndmask_b32_e64 v199, 0, 32, s[48:49]
	v_ldexp_f32 v8, v8, v196
	v_ldexp_f32 v9, v9, v197
	v_ldexp_f32 v10, v10, v198
	v_ldexp_f32 v11, v11, v199
	v_log_f32_e32 v8, v8
	v_log_f32_e32 v9, v9
	v_log_f32_e32 v10, v10
	v_log_f32_e32 v11, v11
	v_mul_f32_e32 v196, s13, v8
	v_mul_f32_e32 v197, s13, v9
	v_mul_f32_e32 v198, s13, v10
	v_mul_f32_e32 v199, s13, v11
	v_fma_f32 v196, v8, s13, -v196
	v_fma_f32 v197, v9, s13, -v197
	v_fma_f32 v198, v10, s13, -v198
	v_fma_f32 v199, v11, s13, -v199
	v_fmac_f32_e32 v196, s99, v8
	v_fmac_f32_e32 v197, s99, v9
	v_fmac_f32_e32 v198, s99, v10
	v_fmac_f32_e32 v199, s99, v11
	v_fmac_f32_e32 v196, s13, v8
	v_fmac_f32_e32 v197, s13, v9
	v_fmac_f32_e32 v198, s13, v10
	v_fmac_f32_e32 v199, s13, v11
	v_cmp_lt_f32_e64 s[4:5], |v8|, s20
	v_cmp_lt_f32_e64 s[50:51], |v9|, s20
	v_cmp_lt_f32_e64 s[54:55], |v10|, s20
	v_cmp_lt_f32_e64 s[56:57], |v11|, s20
	v_cndmask_b32_e64 v8, v8, v196, s[4:5]
	v_cndmask_b32_e64 v9, v9, v197, s[50:51]
	v_cndmask_b32_e64 v10, v10, v198, s[54:55]
	v_cndmask_b32_e64 v11, v11, v199, s[56:57]
	v_cndmask_b32_e64 v196, 0, v177, vcc
	v_cndmask_b32_e64 v197, 0, v177, s[44:45]
	v_cndmask_b32_e64 v198, 0, v177, s[46:47]
	v_cndmask_b32_e64 v199, 0, v177, s[48:49]
	v_sub_f32_e32 v8, v8, v196
	v_sub_f32_e32 v9, v9, v197
	v_sub_f32_e32 v10, v10, v198
	v_sub_f32_e32 v11, v11, v199
	v_cvt_pk_bf16_f32 v16, v16, v17
	v_cvt_pk_bf16_f32 v17, v18, v19
	v_cvt_pk_bf16_f32 v18, v8, v9
	v_cvt_pk_bf16_f32 v19, v10, v11
	v_add_u32_e32 v144, 0x50000, v179
	global_store_dwordx4 v144, v[16:19], s[64:65] offset:256
	s_add_i32 s3, s3, -1
	s_cmp_eq_u32 s3, 0
	s_cbranch_scc1 .Lseg5_done
; __device__ __forceinline__ unsigned cvt_pk_bf16(float lo, float hi) { f32x2_t v = {lo, hi}; bf16x2_t b = __builtin_convertvector(v, bf16x2_t); return __builtin_bit_cast(unsigned, b); }
; __device__ __forceinline__ float sigmoidf_(float v) { return __builtin_amdgcn_rcpf(1.f + __expf(-v)); }
;     __device__ __forceinline__ void operator()(const f32x4 (&acc)[2][2][4][2], const pg8::Unit& u, int wr, int wc, int fr, int fq) const {
;     ...
;                     for (int m = 0; m < 4; ++m) {
;                         bf16_t* p = (bf16_t*)G + (size_t)(row0 + ai * 128 + m * 16) * 1024 + col;
;                         f32x4 a = acc[ai][bj][m][0], b = acc[ai][bj][m][1], ga, gb;
; #pragma unroll
;                         for (int j = 0; j < 4; ++j) { ga[j] = __logf(lb[j] + (1.f - lb[j]) * sigmoidf_(a[j])); gb[j] = __logf(lb[4 + j] + (1.f - lb[4 + j]) * sigmoidf_(b[j])); }
;                         u32x4 w; w.x = cvt_pk_bf16(ga[0], ga[1]); w.y = cvt_pk_bf16(ga[2], ga[3]); w.z = cvt_pk_bf16(gb[0], gb[1]); w.w = cvt_pk_bf16(gb[2], gb[3]);
;                         *(u32x4*)p = w;
.Lseg5_g15:
	v_mul_f32_e32 v4, s98, v4
	v_mul_f32_e32 v5, s98, v5
	v_mul_f32_e32 v6, s98, v6
	v_mul_f32_e32 v7, s98, v7
	v_mul_f32_e32 v0, s98, v0
	v_mul_f32_e32 v1, s98, v1
	v_mul_f32_e32 v2, s98, v2
	v_mul_f32_e32 v3, s98, v3
	v_exp_f32_e32 v4, v4
	v_exp_f32_e32 v5, v5
	v_exp_f32_e32 v6, v6
	v_exp_f32_e32 v7, v7
	v_exp_f32_e32 v0, v0
	v_exp_f32_e32 v1, v1
	v_exp_f32_e32 v2, v2
	v_exp_f32_e32 v3, v3
	v_add_f32_e32 v4, 1.0, v4
	v_add_f32_e32 v5, 1.0, v5
	v_add_f32_e32 v6, 1.0, v6
	v_add_f32_e32 v7, 1.0, v7
	v_add_f32_e32 v0, 1.0, v0
	v_add_f32_e32 v1, 1.0, v1
	v_add_f32_e32 v2, 1.0, v2
	v_add_f32_e32 v3, 1.0, v3
	v_rcp_f32_e32 v4, v4
	v_rcp_f32_e32 v5, v5
	v_rcp_f32_e32 v6, v6
	v_rcp_f32_e32 v7, v7
	v_rcp_f32_e32 v0, v0
	v_rcp_f32_e32 v1, v1
	v_rcp_f32_e32 v2, v2
	v_rcp_f32_e32 v3, v3
	v_fma_f32 v4, v4, v164, v184
	v_fma_f32 v5, v5, v165, v185
	v_fma_f32 v6, v6, v166, v186
	v_fma_f32 v7, v7, v167, v187
	v_fma_f32 v0, v0, v180, v188
	v_fma_f32 v1, v1, v181, v189
	v_fma_f32 v2, v2, v182, v190
	v_fma_f32 v3, v3, v183, v191
	v_cmp_gt_f32_e64 vcc, s12, v4
	v_cmp_gt_f32_e64 s[44:45], s12, v5
	v_cmp_gt_f32_e64 s[46:47], s12, v6
	v_cmp_gt_f32_e64 s[48:49], s12, v7
	v_cndmask_b32_e64 v192, 0, 32, vcc
	v_cndmask_b32_e64 v193, 0, 32, s[44:45]
	v_cndmask_b32_e64 v194, 0, 32, s[46:47]
	v_cndmask_b32_e64 v195, 0, 32, s[48:49]
	v_ldexp_f32 v4, v4, v192
	v_ldexp_f32 v5, v5, v193
	v_ldexp_f32 v6, v6, v194
	v_ldexp_f32 v7, v7, v195
	v_log_f32_e32 v4, v4
	v_log_f32_e32 v5, v5
	v_log_f32_e32 v6, v6
	v_log_f32_e32 v7, v7
	v_mul_f32_e32 v192, s13, v4
	v_mul_f32_e32 v193, s13, v5
	v_mul_f32_e32 v194, s13, v6
	v_mul_f32_e32 v195, s13, v7
	v_fma_f32 v192, v4, s13, -v192
	v_fma_f32 v193, v5, s13, -v193
	v_fma_f32 v194, v6, s13, -v194
	v_fma_f32 v195, v7, s13, -v195
	v_fmac_f32_e32 v192, s99, v4
	v_fmac_f32_e32 v193, s99, v5
	v_fmac_f32_e32 v194, s99, v6
	v_fmac_f32_e32 v195, s99, v7
	v_fmac_f32_e32 v192, s13, v4
	v_fmac_f32_e32 v193, s13, v5
	v_fmac_f32_e32 v194, s13, v6
	v_fmac_f32_e32 v195, s13, v7
	v_cmp_lt_f32_e64 s[4:5], |v4|, s20
	v_cmp_lt_f32_e64 s[50:51], |v5|, s20
	v_cmp_lt_f32_e64 s[54:55], |v6|, s20
	v_cmp_lt_f32_e64 s[56:57], |v7|, s20
	v_cndmask_b32_e64 v4, v4, v192, s[4:5]
	v_cndmask_b32_e64 v5, v5, v193, s[50:51]
	v_cndmask_b32_e64 v6, v6, v194, s[54:55]
	v_cndmask_b32_e64 v7, v7, v195, s[56:57]
	v_cndmask_b32_e64 v192, 0, v177, vcc
	v_cndmask_b32_e64 v193, 0, v177, s[44:45]
	v_cndmask_b32_e64 v194, 0, v177, s[46:47]
	v_cndmask_b32_e64 v195, 0, v177, s[48:49]
	v_sub_f32_e32 v4, v4, v192
	v_sub_f32_e32 v5, v5, v193
	v_sub_f32_e32 v6, v6, v194
	v_sub_f32_e32 v7, v7, v195
	v_cmp_gt_f32_e64 vcc, s12, v0
	v_cmp_gt_f32_e64 s[44:45], s12, v1
	v_cmp_gt_f32_e64 s[46:47], s12, v2
	v_cmp_gt_f32_e64 s[48:49], s12, v3
	v_cndmask_b32_e64 v196, 0, 32, vcc
	v_cndmask_b32_e64 v197, 0, 32, s[44:45]
	v_cndmask_b32_e64 v198, 0, 32, s[46:47]
	v_cndmask_b32_e64 v199, 0, 32, s[48:49]
	v_ldexp_f32 v0, v0, v196
	v_ldexp_f32 v1, v1, v197
	v_ldexp_f32 v2, v2, v198
	v_ldexp_f32 v3, v3, v199
	v_log_f32_e32 v0, v0
	v_log_f32_e32 v1, v1
	v_log_f32_e32 v2, v2
	v_log_f32_e32 v3, v3
	v_mul_f32_e32 v196, s13, v0
	v_mul_f32_e32 v197, s13, v1
	v_mul_f32_e32 v198, s13, v2
	v_mul_f32_e32 v199, s13, v3
	v_fma_f32 v196, v0, s13, -v196
	v_fma_f32 v197, v1, s13, -v197
	v_fma_f32 v198, v2, s13, -v198
	v_fma_f32 v199, v3, s13, -v199
	v_fmac_f32_e32 v196, s99, v0
	v_fmac_f32_e32 v197, s99, v1
	v_fmac_f32_e32 v198, s99, v2
	v_fmac_f32_e32 v199, s99, v3
	v_fmac_f32_e32 v196, s13, v0
	v_fmac_f32_e32 v197, s13, v1
	v_fmac_f32_e32 v198, s13, v2
	v_fmac_f32_e32 v199, s13, v3
	v_cmp_lt_f32_e64 s[4:5], |v0|, s20
	v_cmp_lt_f32_e64 s[50:51], |v1|, s20
	v_cmp_lt_f32_e64 s[54:55], |v2|, s20
	v_cmp_lt_f32_e64 s[56:57], |v3|, s20
	v_cndmask_b32_e64 v0, v0, v196, s[4:5]
	v_cndmask_b32_e64 v1, v1, v197, s[50:51]
	v_cndmask_b32_e64 v2, v2, v198, s[54:55]
	v_cndmask_b32_e64 v3, v3, v199, s[56:57]
	v_cndmask_b32_e64 v196, 0, v177, vcc
	v_cndmask_b32_e64 v197, 0, v177, s[44:45]
	v_cndmask_b32_e64 v198, 0, v177, s[46:47]
	v_cndmask_b32_e64 v199, 0, v177, s[48:49]
	v_sub_f32_e32 v0, v0, v196
	v_sub_f32_e32 v1, v1, v197
	v_sub_f32_e32 v2, v2, v198
	v_sub_f32_e32 v3, v3, v199
	v_cvt_pk_bf16_f32 v4, v4, v5
	v_cvt_pk_bf16_f32 v5, v6, v7
	v_cvt_pk_bf16_f32 v6, v0, v1
	v_cvt_pk_bf16_f32 v7, v2, v3
	v_add_u32_e32 v155, 0x58000, v179
	global_store_dwordx4 v155, v[4:7], s[64:65] offset:256
	s_add_i32 s3, s3, -1
	s_cmp_eq_u32 s3, 0
	s_cbranch_scc1 .Lseg5_done
	s_branch .Lseg5_g0
.Lseg5_done:
	v_readlane_b32 s44, v250, 1
	v_readlane_b32 s45, v250, 2
	v_readlane_b32 s46, v250, 17
	v_readlane_b32 s47, v250, 18
	v_readlane_b32 s48, v250, 5
	v_readlane_b32 s49, v250, 6
	v_readlane_b32 s50, v250, 7
	v_readlane_b32 s51, v250, 8
	v_readlane_b32 s52, v250, 9
	v_readlane_b32 s53, v250, 10
	s_mov_b64 s[54:55], 0x40000
	s_mov_b64 s[56:57], 0x48000
	v_readlane_b32 s58, v250, 15
	v_readlane_b32 s59, v250, 16
	s_mov_b32 s3, 0x58000
	s_nop 4
	s_mov_b64 s[4:5], 0

; __global__ void __launch_bounds__(512, 2) mk_fwd(Args args) {
	.amdhsa_kernel _Z6mk_fwd4Args
		.amdhsa_group_segment_fixed_size 0
		.amdhsa_private_segment_fixed_size 0
		.amdhsa_kernarg_size 360
		.amdhsa_user_sgpr_count 2
		.amdhsa_user_sgpr_dispatch_ptr 0
		.amdhsa_user_sgpr_queue_ptr 0
		.amdhsa_user_sgpr_kernarg_segment_ptr 1
		.amdhsa_user_sgpr_dispatch_id 0
		.amdhsa_user_sgpr_kernarg_preload_length 0
		.amdhsa_user_sgpr_kernarg_preload_offset 0
		.amdhsa_user_sgpr_private_segment_size 0
		.amdhsa_uses_dynamic_stack 0
		.amdhsa_enable_private_segment 0
		.amdhsa_system_sgpr_workgroup_id_x 1
		.amdhsa_system_sgpr_workgroup_id_y 0
		.amdhsa_system_sgpr_workgroup_id_z 0
		.amdhsa_system_sgpr_workgroup_info 0
		.amdhsa_system_vgpr_workitem_id 2
		.amdhsa_next_free_vgpr 251
		.amdhsa_next_free_sgpr 102
		.amdhsa_accum_offset 252
		.amdhsa_reserve_vcc 1
		.amdhsa_float_round_mode_32 0
		.amdhsa_float_round_mode_16_64 0
		.amdhsa_float_denorm_mode_32 3
		.amdhsa_float_denorm_mode_16_64 3
		.amdhsa_dx10_clamp 1
		.amdhsa_ieee_mode 1
		.amdhsa_fp16_overflow 0
		.amdhsa_tg_split 0
		.amdhsa_exception_fp_ieee_invalid_op 0
		.amdhsa_exception_fp_denorm_src 0
		.amdhsa_exception_fp_ieee_div_zero 0
		.amdhsa_exception_fp_ieee_overflow 0
		.amdhsa_exception_fp_ieee_underflow 0
		.amdhsa_exception_fp_ieee_inexact 0
		.amdhsa_exception_int_div_zero 0
	.end_amdhsa_kernel

; __global__ void __launch_bounds__(512, 2) mk_fwd(Args args) {
amdhsa.kernels:
  - .agpr_count:     0
    .args:
      - .offset:         0
        .size:           104
        .value_kind:     by_value
      - .offset:         104
        .size:           4
        .value_kind:     hidden_block_count_x
      - .offset:         108
        .size:           4
        .value_kind:     hidden_block_count_y
      - .offset:         112
        .size:           4
        .value_kind:     hidden_block_count_z
      - .offset:         116
        .size:           2
        .value_kind:     hidden_group_size_x
      - .offset:         118
        .size:           2
        .value_kind:     hidden_group_size_y
      - .offset:         120
        .size:           2
        .value_kind:     hidden_group_size_z
      - .offset:         122
        .size:           2
        .value_kind:     hidden_remainder_x
      - .offset:         124
        .size:           2
        .value_kind:     hidden_remainder_y
      - .offset:         126
        .size:           2
        .value_kind:     hidden_remainder_z
      - .offset:         144
        .size:           8
        .value_kind:     hidden_global_offset_x
      - .offset:         152
        .size:           8
        .value_kind:     hidden_global_offset_y
      - .offset:         160
        .size:           8
        .value_kind:     hidden_global_offset_z
      - .offset:         168
        .size:           2
        .value_kind:     hidden_grid_dims
      - .offset:         192
        .size:           8
        .value_kind:     hidden_multigrid_sync_arg
      - .offset:         224
        .size:           4
        .value_kind:     hidden_dynamic_lds_size
    .group_segment_fixed_size: 0
    .kernarg_segment_align: 8
    .kernarg_segment_size: 360
    .language:       OpenCL C
    .language_version:
      - 2
      - 0
    .max_flat_workgroup_size: 512
    .name:           _Z6mk_fwd4Args
    .private_segment_fixed_size: 0
    .sgpr_count:     108
    .sgpr_spill_count: 26
    .symbol:         _Z6mk_fwd4Args.kd
    .uniform_work_group_size: 1
    .uses_dynamic_stack: false
    .vgpr_count:     251
    .vgpr_spill_count: 0
    .wavefront_size: 64
